# w_out, up and down GEMM K loops: first iteration peeled with C=0 on the first MFMA of every accumulator, the 128 zeroing v_mov per unit are gone
# speedup vs baseline: 1.0048x; 1.0023x over previous
; #define PG8_WAIT_V(n) asm volatile("s_waitcnt vmcnt(" #n ")" ::: "memory")
; #define PG8_BAR __builtin_amdgcn_s_barrier()
;     const int tid = threadIdx.x, wid = __builtin_amdgcn_readfirstlane(tid >> 6), lane = tid & 63, wr = wid >> 2, wc = wid & 3, fr = lane & 15, fq = lane >> 4;
;     const int nt = K / BK;
;     unsigned voffA[2], voffB[2];
; #pragma unroll
;     for (int i = 0; i < 2; ++i) { int R, C; stage_rc(tid * 16 + i * 8192, R, C); const int Rb = Epi::PERM64 ? (64 * (R >> 5) + perm32(R & 31)) : Epi::PERM ? ((R & ~31) + perm32(R & 31)) : R;
;         voffA[i] = (unsigned)(R * K + C) * 2u; voffB[i] = (unsigned)(Rb * K + C) * 2u; }
;     const size_t kstep = (size_t)(BK * 2);
;     const size_t hstep = (size_t)HALF * K * 2;
;     const size_t hstepB = Epi::PERM64 ? (size_t)32 * K * 2 : hstep;
;     const unsigned ldsw = (unsigned)wid * 1024u;
;     const int aoff = lds_byte(wr * 64 + fr, fq * 8), boff = lds_byte(wc * 32 + fr, fq * 8);
;     ...
;     Unit cur, nxt; int ui = 0;
;     if (!S.next(0, cur)) return;
;     f32x4 acc[2][2][4][2];
;     if constexpr (!DE) {
; #pragma unroll
;     for (int a = 0; a < 2; ++a)
; #pragma unroll
;         for (int b = 0; b < 2; ++b)
; #pragma unroll
;             for (int m = 0; m < 4; ++m)
; #pragma unroll
;                 for (int n = 0; n < 2; ++n) acc[a][b][m][n] = (f32x4){0.f, 0.f, 0.f, 0.f};
;     }
;     bf16x8 At[4][2], B0[2][2], B1[2][2];
;     const char* cA = S.a_ptr(cur); const char* cB = S.b_ptr(cur);
;     S.a_ready(cur);
;     if constexpr (SP2) {
;         PG8_STAGE(PG8_SB(0, 0), cB, voffB); PG8_STAGE(PG8_SB(0, 1), cB + hstepB, voffB); PG8_STAGE(PG8_SA(0, 0), cA, voffA); PG8_STAGE(PG8_SA(0, 1), cA + hstep, voffA);
;         if (wr == 1) PG8_BAR;
;         PG8_WAIT_V(2); PG8_BAR;
;         PG8_STAGE(PG8_SB(1, 0), cB + kstep, voffB); PG8_STAGE(PG8_SA(1, 0), cA + kstep, voffA); PG8_STAGE(PG8_SB(1, 1), cB + hstepB + kstep, voffB);
;         PG8_WAIT_V(6); PG8_BAR;
;     } else {
;         PG8_STAGE(PG8_SB(0, 0), cB, voffB); PG8_STAGE(PG8_SA(0, 0), cA, voffA); PG8_STAGE(PG8_SB(0, 1), cB + hstepB, voffB); PG8_STAGE(PG8_SA(0, 1), cA + hstep, voffA);
;         if (wr == 1) PG8_BAR;
;         PG8_WAIT_V(4); PG8_BAR;
;         PG8_STAGE(PG8_SB(1, 0), cB + kstep, voffB); PG8_STAGE(PG8_SA(1, 0), cA + kstep, voffA); PG8_STAGE(PG8_SB(1, 1), cB + hstepB + kstep, voffB);
;         PG8_WAIT_V(6); PG8_BAR;
.LBB0_790:
	v_bfe_u32 v139, v0, 4, 2
	v_and_b32_e32 v2, 15, v0
	v_lshlrev_b32_e32 v3, 4, v139
	v_lshlrev_b32_e32 v4, 2, v0
	s_and_b32 s11, s2, 3
	v_lshl_or_b32 v134, s3, 6, v2
	v_lshl_or_b32 v2, v2, 6, v3
	s_lshl_b32 s2, s3, 13
	v_and_b32_e32 v4, 32, v4
	v_bitop3_b32 v5, v2, s2, v4 bitop3:0xde
	v_lshlrev_b32_e32 v2, 6, v0
	s_movk_i32 s2, 0x3c0
	v_and_or_b32 v2, v2, s2, v3
	s_lshl_b32 s2, s11, 12
	v_bitop3_b32 v140, s2, v2, v4 bitop3:0xf6
	s_add_u32 s2, s12, 0x80
	s_addc_u32 s3, s13, 0
	v_mov_b32_e32 v2, v136
	s_waitcnt vmcnt(2)
	s_barrier
	s_add_i32 m0, s33, 0x18000
	s_sext_i32_i8 s0, s0
	global_load_lds_dwordx4 v2, s[2:3]
	v_mov_b32_e32 v2, v138
	s_add_i32 m0, s33, 0x1a000
	v_mov_b64_e32 v[130:131], 0x100
	global_load_lds_dwordx4 v2, s[2:3]
	s_add_u32 s2, s14, 0x80
	s_addc_u32 s3, s15, 0
	v_mov_b32_e32 v2, v135
	s_add_i32 s38, s33, 0x8000
	s_mov_b32 m0, s38
	s_add_i32 s39, s33, 0xa000
	global_load_lds_dwordx4 v2, s[2:3]
	v_mov_b32_e32 v2, v137
	s_mov_b32 m0, s39
	v_mov_b64_e32 v[132:133], 0xff
	global_load_lds_dwordx4 v2, s[2:3]
	s_add_u32 s2, s12, 0x40080
	s_addc_u32 s3, s13, 0
	v_mov_b32_e32 v2, v136
	s_add_i32 m0, s33, 0x1c000
	s_add_i32 s40, 0, 0x10000
	global_load_lds_dwordx4 v2, s[2:3]
	v_mov_b32_e32 v2, v138
	s_add_i32 m0, s33, 0x1e000
	s_add_i32 s41, 0, 0x14000
	global_load_lds_dwordx4 v2, s[2:3]
	s_waitcnt vmcnt(6)
	v_add_u32_e32 v141, 0, v5
	s_barrier
	s_branch .LBB0_792

;     __device__ __forceinline__ bool next(int i, Unit& u) const { const long L = (long)i * G + c; if (L >= (long)nM * nN) return false; static_tile((int)L, nM, nN, u.pm, u.pn); u.br = 0; return true; }
; #define PG8_WAIT_V(n) asm volatile("s_waitcnt vmcnt(" #n ")" ::: "memory")
;     ...
;     for (;;) {
;         const bool has_next = S.next(ui + 1, nxt);
;         if (GP) gpU = __builtin_amdgcn_s_memrealtime();
;         const char* nA = has_next ? S.a_ptr(nxt) : cA; const char* nB = has_next ? S.b_ptr(nxt) : cB;
;         for (int t = 0; t < nt; t += 2) {
;             const bool last = (t == nt - 2);
;             if (GP && t == 2) gp1 = __builtin_amdgcn_s_memrealtime();
;             const char* a1 = cA + (size_t)(t + 1) * kstep;
;             const char* a2 = last ? nA : cA + (size_t)(t + 2) * kstep; const char* b2 = last ? nB : cB + (size_t)(t + 2) * kstep;
;             const char* a3 = a2 + kstep; const char* b3 = b2 + kstep;
;             if (last && has_next) S.a_ready(nxt);
;             if constexpr (SP2) {
;             PG8_LDB(B0, 0, 0); PG8_LDB(B1, 0, 1); PG8_SCHED; PG8_LDA(At, 0, 0); PG8_STAGE(PG8_SA(1, 1), a1 + hstep, voffA);
;             PG8_WAIT_V(8); PG8_WAIT_L(0); PG8_BAR; PG8_MMA(0, 0, At, B0); PG8_MMA(0, 1, At, B1); PG8_BAR; PG8_SCHED;
;             PG8_LDA(At, 0, 1); PG8_STAGE(PG8_SB(0, 0), b2, voffB); PG8_STAGE(PG8_SB(0, 1), b2 + hstepB, voffB); PG8_STAGE(PG8_SA(0, 0), a2, voffA);
;             PG8_WAIT_V(8); PG8_WAIT_L(0); PG8_BAR; PG8_MMA(1, 0, At, B0); PG8_MMA(1, 1, At, B1); PG8_BAR; PG8_SCHED;
;             PG8_LDB(B0, 1, 0); PG8_LDB(B1, 1, 1); PG8_SCHED; PG8_LDA(At, 1, 0); PG8_STAGE(PG8_SA(0, 1), a2 + hstep, voffA);
;             PG8_WAIT_V(8); PG8_WAIT_L(0); PG8_BAR; PG8_MMA(0, 0, At, B0); PG8_MMA(0, 1, At, B1); PG8_BAR; PG8_SCHED;
;             PG8_LDA(At, 1, 1); PG8_STAGE(PG8_SB(1, 0), b3, voffB); PG8_STAGE(PG8_SB(1, 1), b3 + hstepB, voffB); PG8_STAGE(PG8_SA(1, 0), a3, voffA);
;             PG8_WAIT_V(8); PG8_WAIT_L(0); PG8_BAR; PG8_MMA(1, 0, At, B0); PG8_MMA(1, 1, At, B1); PG8_BAR; PG8_SCHED;
;     ...
;         if constexpr (!Epi::KEEP_ACC) {
; #pragma unroll
;         for (int a = 0; a < 2; ++a)
; #pragma unroll
;             for (int b = 0; b < 2; ++b)
; #pragma unroll
;                 for (int m = 0; m < 4; ++m)
; #pragma unroll
;                     for (int n = 0; n < 2; ++n) acc[a][b][m][n] = (f32x4){0.f, 0.f, 0.f, 0.f};
;         }
.LBB0_798:
	s_ashr_i32 s19, s18, 31
	s_lshl_b64 s[2:3], s[18:19], 19
	v_readlane_b32 s20, v247, 53
	v_readlane_b32 s21, v247, 54
	s_add_u32 s2, s20, s2
	s_addc_u32 s3, s21, s3
	s_and_b64 s[20:21], s[4:5], exec
	s_cselect_b32 s19, s3, s15
	s_cselect_b32 s43, s2, s14
	s_ashr_i32 s17, s16, 31
	s_lshl_b64 s[20:21], s[16:17], 19
	s_add_u32 s20, s50, s20
	s_addc_u32 s21, s51, s21
	s_and_b64 s[22:23], s[4:5], exec
	s_cselect_b32 s17, s21, s13
	s_cselect_b32 s44, s20, s12
	s_mov_b32 s45, -2
	s_mov_b64 s[22:23], 0
	s_add_u32 s46, s14, s22
	s_addc_u32 s47, s15, s23
	s_add_u32 s24, s46, 0x100
	s_addc_u32 s25, s47, 0
	v_add_u32_e32 v154, s40, v140
	v_add_u32_e32 v170, s41, v140
	s_add_u32 s26, s12, s22
	ds_read_b128 v[142:145], v154
	ds_read_b128 v[146:149], v154 offset:1024
	ds_read_b128 v[150:153], v154 offset:2048
	ds_read_b128 v[154:157], v154 offset:3072
	ds_read_b128 v[158:161], v170
	ds_read_b128 v[162:165], v170 offset:1024
	ds_read_b128 v[166:169], v170 offset:2048
	ds_read_b128 v[170:173], v170 offset:3072
	s_addc_u32 s27, s13, s23
	s_add_u32 s26, s26, 0x100
	s_addc_u32 s27, s27, 0
	s_cmp_eq_u32 s45, 12
	s_cselect_b32 s28, s43, s24
	s_cselect_b32 s29, s19, s25
	s_cselect_b32 s26, s44, s26
	s_cselect_b32 s27, s17, s27
	s_add_u32 s24, s28, 0x80
	s_addc_u32 s25, s29, 0
	s_add_u32 s46, s46, 0x40080
	s_addc_u32 s47, s47, 0
	v_mov_b32_e32 v206, v135
	s_waitcnt lgkmcnt(7)
	ds_read_b128 v[174:177], v141
	ds_read_b128 v[178:181], v141 offset:1024
	ds_read_b128 v[182:185], v141 offset:2048
	ds_read_b128 v[186:189], v141 offset:3072
	ds_read_b128 v[190:193], v141 offset:4096
	ds_read_b128 v[194:197], v141 offset:5120
	ds_read_b128 v[198:201], v141 offset:6144
	ds_read_b128 v[202:205], v141 offset:7168
	s_add_i32 m0, s33, 0xc000
	s_nop 0
	global_load_lds_dwordx4 v206, s[46:47]
	v_mov_b32_e32 v206, v137
	s_add_i32 m0, s33, 0xe000
	s_nop 0
	global_load_lds_dwordx4 v206, s[46:47]
	s_waitcnt vmcnt(8)
	s_waitcnt lgkmcnt(0)
	s_barrier
	s_setprio 1
	s_waitcnt lgkmcnt(0)
	v_mfma_f32_16x16x32_bf16 v[126:129], v[142:145], v[174:177], 0
	v_mfma_f32_16x16x32_bf16 v[122:125], v[150:153], v[174:177], 0
	v_mfma_f32_16x16x32_bf16 v[110:113], v[142:145], v[182:185], 0
	v_mfma_f32_16x16x32_bf16 v[106:109], v[150:153], v[182:185], 0
	v_mfma_f32_16x16x32_bf16 v[94:97], v[142:145], v[190:193], 0
	v_mfma_f32_16x16x32_bf16 v[90:93], v[150:153], v[190:193], 0
	v_mfma_f32_16x16x32_bf16 v[78:81], v[142:145], v[198:201], 0
	v_mfma_f32_16x16x32_bf16 v[74:77], v[150:153], v[198:201], 0
	v_mfma_f32_16x16x32_bf16 v[126:129], v[146:149], v[178:181], v[126:129]
	v_mfma_f32_16x16x32_bf16 v[122:125], v[154:157], v[178:181], v[122:125]
	v_mfma_f32_16x16x32_bf16 v[110:113], v[146:149], v[186:189], v[110:113]
	v_mfma_f32_16x16x32_bf16 v[106:109], v[154:157], v[186:189], v[106:109]
	v_mfma_f32_16x16x32_bf16 v[94:97], v[146:149], v[194:197], v[94:97]
	v_mfma_f32_16x16x32_bf16 v[90:93], v[154:157], v[194:197], v[90:93]
	v_mfma_f32_16x16x32_bf16 v[78:81], v[146:149], v[202:205], v[78:81]
	v_mfma_f32_16x16x32_bf16 v[74:77], v[154:157], v[202:205], v[74:77]
	s_setprio 0
	s_setprio 1
	v_mfma_f32_16x16x32_bf16 v[118:121], v[158:161], v[174:177], 0
	v_mfma_f32_16x16x32_bf16 v[114:117], v[166:169], v[174:177], 0
	v_mfma_f32_16x16x32_bf16 v[102:105], v[158:161], v[182:185], 0
	v_mfma_f32_16x16x32_bf16 v[98:101], v[166:169], v[182:185], 0
	v_mfma_f32_16x16x32_bf16 v[86:89], v[158:161], v[190:193], 0
	v_mfma_f32_16x16x32_bf16 v[82:85], v[166:169], v[190:193], 0
	v_mfma_f32_16x16x32_bf16 v[70:73], v[158:161], v[198:201], 0
	v_mfma_f32_16x16x32_bf16 v[66:69], v[166:169], v[198:201], 0
	v_mfma_f32_16x16x32_bf16 v[118:121], v[162:165], v[178:181], v[118:121]
	v_mfma_f32_16x16x32_bf16 v[114:117], v[170:173], v[178:181], v[114:117]
	v_mfma_f32_16x16x32_bf16 v[102:105], v[162:165], v[186:189], v[102:105]
	v_mfma_f32_16x16x32_bf16 v[98:101], v[170:173], v[186:189], v[98:101]
	v_mfma_f32_16x16x32_bf16 v[86:89], v[162:165], v[194:197], v[86:89]
	v_mfma_f32_16x16x32_bf16 v[82:85], v[170:173], v[194:197], v[82:85]
	v_mfma_f32_16x16x32_bf16 v[70:73], v[162:165], v[202:205], v[70:73]
	v_mfma_f32_16x16x32_bf16 v[66:69], v[170:173], v[202:205], v[66:69]
	s_setprio 0
	s_barrier
	s_mov_b64 s[46:47], s[26:27]
	v_mov_b32_e32 v206, v136
	s_add_i32 s48, s40, s1
	ds_read_b128 v[174:177], v141 offset:16384
	ds_read_b128 v[178:181], v141 offset:17408
	ds_read_b128 v[182:185], v141 offset:18432
	ds_read_b128 v[186:189], v141 offset:19456
	ds_read_b128 v[190:193], v141 offset:20480
	ds_read_b128 v[194:197], v141 offset:21504
	ds_read_b128 v[198:201], v141 offset:22528
	ds_read_b128 v[202:205], v141 offset:23552
	s_mov_b32 m0, s48
	s_nop 0
	global_load_lds_dwordx4 v206, s[46:47]
	v_mov_b32_e32 v206, v138
	s_add_i32 m0, s48, 0x2000
	s_nop 0
	global_load_lds_dwordx4 v206, s[46:47]
	s_add_u32 s46, s26, 0x40000
	s_addc_u32 s47, s27, 0
	v_mov_b32_e32 v206, v136
	s_add_i32 s48, s41, s1
	s_mov_b32 m0, s48
	s_nop 0
	global_load_lds_dwordx4 v206, s[46:47]
	v_mov_b32_e32 v206, v138
	s_add_i32 m0, s48, 0x2000
	s_nop 0
	global_load_lds_dwordx4 v206, s[46:47]
	s_mov_b64 s[46:47], s[28:29]
	v_mov_b32_e32 v206, v135
	s_mov_b32 m0, s33
	s_nop 0
	global_load_lds_dwordx4 v206, s[46:47]
	v_mov_b32_e32 v206, v137
	s_mov_b32 m0, s34
	s_nop 0
	global_load_lds_dwordx4 v206, s[46:47]
	s_waitcnt vmcnt(8)
	s_waitcnt lgkmcnt(0)
	s_barrier
; #define PG8_STAGE(bufoff, gbase, voff) do { const char* gb_ = (const char*)(gbase); asm volatile("" : "+s"(gb_)); _Pragma("unroll") for (int _i = 0; _i < 2; ++_i) { unsigned vo_ = (voff)[_i]; asm volatile("" : "+v"(vo_)); \
;         __builtin_amdgcn_global_load_lds((const unsigned*)(gb_ + vo_), (PG8_LAS unsigned*)(lds + (bufoff) + ldsw + _i * 8192), 16, 0, 0); } } while (0)
; #define PG8_LDA(dst, b, h) do { _Pragma("unroll") for (int m = 0; m < 4; ++m) _Pragma("unroll") for (int k = 0; k < 2; ++k) dst[m][k] = *(const PG8_LAS bf16x8*)(lds + PG8_SA(b, h) + aoff + m * 2048 + k * 1024); } while (0)
; #define PG8_LDB(dst, b, h) do { _Pragma("unroll") for (int n = 0; n < 2; ++n) _Pragma("unroll") for (int k = 0; k < 2; ++k) dst[n][k] = *(const PG8_LAS bf16x8*)(lds + PG8_SB(b, h) + boff + n * 2048 + k * 1024); } while (0)
; #define PG8_MMA(ai, bj, At, Bt) do { __builtin_amdgcn_s_setprio(1); _Pragma("unroll") for (int m = 0; m < 4; ++m) _Pragma("unroll") for (int n = 0; n < 2; ++n) _Pragma("unroll") for (int k = 0; k < 2; ++k) \
;         acc[ai][bj][m][n] = __builtin_amdgcn_mfma_f32_16x16x32_bf16(Bt[n][k], At[m][k], acc[ai][bj][m][n], 0, 0, 0); __builtin_amdgcn_s_setprio(0); } while (0)
; #define PG8_WAIT_V(n) asm volatile("s_waitcnt vmcnt(" #n ")" ::: "memory")
; #define PG8_BAR __builtin_amdgcn_s_barrier()
;     ...
;             if constexpr (SP2) {
;             PG8_LDB(B0, 0, 0); PG8_LDB(B1, 0, 1); PG8_SCHED; PG8_LDA(At, 0, 0); PG8_STAGE(PG8_SA(1, 1), a1 + hstep, voffA);
;             PG8_WAIT_V(8); PG8_WAIT_L(0); PG8_BAR; PG8_MMA(0, 0, At, B0); PG8_MMA(0, 1, At, B1); PG8_BAR; PG8_SCHED;
;             PG8_LDA(At, 0, 1); PG8_STAGE(PG8_SB(0, 0), b2, voffB); PG8_STAGE(PG8_SB(0, 1), b2 + hstepB, voffB); PG8_STAGE(PG8_SA(0, 0), a2, voffA);
;             PG8_WAIT_V(8); PG8_WAIT_L(0); PG8_BAR; PG8_MMA(1, 0, At, B0); PG8_MMA(1, 1, At, B1); PG8_BAR; PG8_SCHED;
;             PG8_LDB(B0, 1, 0); PG8_LDB(B1, 1, 1); PG8_SCHED; PG8_LDA(At, 1, 0); PG8_STAGE(PG8_SA(0, 1), a2 + hstep, voffA);
;             PG8_WAIT_V(8); PG8_WAIT_L(0); PG8_BAR; PG8_MMA(0, 0, At, B0); PG8_MMA(0, 1, At, B1); PG8_BAR; PG8_SCHED;
;             PG8_LDA(At, 1, 1); PG8_STAGE(PG8_SB(1, 0), b3, voffB); PG8_STAGE(PG8_SB(1, 1), b3 + hstepB, voffB); PG8_STAGE(PG8_SA(1, 0), a3, voffA);
;             PG8_WAIT_V(8); PG8_WAIT_L(0); PG8_BAR; PG8_MMA(1, 0, At, B0); PG8_MMA(1, 1, At, B1); PG8_BAR; PG8_SCHED;
	s_setprio 1
	s_waitcnt lgkmcnt(0)
	v_mfma_f32_16x16x32_bf16 v[62:65], v[142:145], v[174:177], 0
	v_mfma_f32_16x16x32_bf16 v[58:61], v[150:153], v[174:177], 0
	v_mfma_f32_16x16x32_bf16 v[46:49], v[142:145], v[182:185], 0
	v_mfma_f32_16x16x32_bf16 v[42:45], v[150:153], v[182:185], 0
	v_mfma_f32_16x16x32_bf16 v[30:33], v[142:145], v[190:193], 0
	v_mfma_f32_16x16x32_bf16 v[26:29], v[150:153], v[190:193], 0
	v_mfma_f32_16x16x32_bf16 v[14:17], v[142:145], v[198:201], 0
	v_mfma_f32_16x16x32_bf16 v[10:13], v[150:153], v[198:201], 0
	v_mfma_f32_16x16x32_bf16 v[62:65], v[146:149], v[178:181], v[62:65]
	v_mfma_f32_16x16x32_bf16 v[58:61], v[154:157], v[178:181], v[58:61]
	v_mfma_f32_16x16x32_bf16 v[46:49], v[146:149], v[186:189], v[46:49]
	v_mfma_f32_16x16x32_bf16 v[42:45], v[154:157], v[186:189], v[42:45]
	v_mfma_f32_16x16x32_bf16 v[30:33], v[146:149], v[194:197], v[30:33]
	v_mfma_f32_16x16x32_bf16 v[26:29], v[154:157], v[194:197], v[26:29]
	v_mfma_f32_16x16x32_bf16 v[14:17], v[146:149], v[202:205], v[14:17]
	v_mfma_f32_16x16x32_bf16 v[10:13], v[154:157], v[202:205], v[10:13]
	s_setprio 0
	s_setprio 1
	v_mfma_f32_16x16x32_bf16 v[54:57], v[158:161], v[174:177], 0
	v_mfma_f32_16x16x32_bf16 v[50:53], v[166:169], v[174:177], 0
	v_mfma_f32_16x16x32_bf16 v[38:41], v[158:161], v[182:185], 0
	v_mfma_f32_16x16x32_bf16 v[34:37], v[166:169], v[182:185], 0
	v_mfma_f32_16x16x32_bf16 v[22:25], v[158:161], v[190:193], 0
	v_mfma_f32_16x16x32_bf16 v[18:21], v[166:169], v[190:193], 0
	v_mfma_f32_16x16x32_bf16 v[6:9], v[158:161], v[198:201], 0
	v_mfma_f32_16x16x32_bf16 v[2:5], v[166:169], v[198:201], 0
	v_mfma_f32_16x16x32_bf16 v[54:57], v[162:165], v[178:181], v[54:57]
	v_mfma_f32_16x16x32_bf16 v[50:53], v[170:173], v[178:181], v[50:53]
	v_mfma_f32_16x16x32_bf16 v[38:41], v[162:165], v[186:189], v[38:41]
	v_mfma_f32_16x16x32_bf16 v[34:37], v[170:173], v[186:189], v[34:37]
	v_mfma_f32_16x16x32_bf16 v[22:25], v[162:165], v[194:197], v[22:25]
	v_mfma_f32_16x16x32_bf16 v[18:21], v[170:173], v[194:197], v[18:21]
	v_mfma_f32_16x16x32_bf16 v[6:9], v[162:165], v[202:205], v[6:9]
	v_mfma_f32_16x16x32_bf16 v[2:5], v[170:173], v[202:205], v[2:5]
	s_setprio 0
	s_barrier
	s_add_i32 s46, 0, 0x18000
	s_add_i32 s47, 0, 0x1c000
	v_add_u32_e32 v154, s46, v140
	v_add_u32_e32 v170, s47, v140
	ds_read_b128 v[142:145], v154
	ds_read_b128 v[146:149], v154 offset:1024
	ds_read_b128 v[150:153], v154 offset:2048
	ds_read_b128 v[154:157], v154 offset:3072
	ds_read_b128 v[158:161], v170
	ds_read_b128 v[162:165], v170 offset:1024
	ds_read_b128 v[166:169], v170 offset:2048
	ds_read_b128 v[170:173], v170 offset:3072
	s_add_u32 s28, s28, 0x40000
	s_addc_u32 s29, s29, 0
	v_mov_b32_e32 v206, v135
	s_mov_b32 m0, s35
	ds_read_b128 v[174:177], v141 offset:32768
	ds_read_b128 v[178:181], v141 offset:33792
	ds_read_b128 v[182:185], v141 offset:34816
	ds_read_b128 v[186:189], v141 offset:35840
	ds_read_b128 v[190:193], v141 offset:36864
	ds_read_b128 v[194:197], v141 offset:37888
	ds_read_b128 v[198:201], v141 offset:38912
	ds_read_b128 v[202:205], v141 offset:39936
	s_nop 0
	global_load_lds_dwordx4 v206, s[28:29]
	v_mov_b32_e32 v206, v137
	s_mov_b32 m0, s36
	s_nop 0
	global_load_lds_dwordx4 v206, s[28:29]
	s_waitcnt vmcnt(8)
	s_waitcnt lgkmcnt(0)
	s_barrier
	s_setprio 1
	s_waitcnt lgkmcnt(0)
	v_mfma_f32_16x16x32_bf16 v[126:129], v[142:145], v[174:177], v[126:129]
	v_mfma_f32_16x16x32_bf16 v[122:125], v[150:153], v[174:177], v[122:125]
	v_mfma_f32_16x16x32_bf16 v[110:113], v[142:145], v[182:185], v[110:113]
	v_mfma_f32_16x16x32_bf16 v[106:109], v[150:153], v[182:185], v[106:109]
	v_mfma_f32_16x16x32_bf16 v[94:97], v[142:145], v[190:193], v[94:97]
	v_mfma_f32_16x16x32_bf16 v[90:93], v[150:153], v[190:193], v[90:93]
	v_mfma_f32_16x16x32_bf16 v[78:81], v[142:145], v[198:201], v[78:81]
	v_mfma_f32_16x16x32_bf16 v[74:77], v[150:153], v[198:201], v[74:77]
	v_mfma_f32_16x16x32_bf16 v[126:129], v[146:149], v[178:181], v[126:129]
	v_mfma_f32_16x16x32_bf16 v[122:125], v[154:157], v[178:181], v[122:125]
	v_mfma_f32_16x16x32_bf16 v[110:113], v[146:149], v[186:189], v[110:113]
	v_mfma_f32_16x16x32_bf16 v[106:109], v[154:157], v[186:189], v[106:109]
	v_mfma_f32_16x16x32_bf16 v[94:97], v[146:149], v[194:197], v[94:97]
	v_mfma_f32_16x16x32_bf16 v[90:93], v[154:157], v[194:197], v[90:93]
	v_mfma_f32_16x16x32_bf16 v[78:81], v[146:149], v[202:205], v[78:81]
	v_mfma_f32_16x16x32_bf16 v[74:77], v[154:157], v[202:205], v[74:77]
	s_setprio 0
	s_setprio 1
	v_mfma_f32_16x16x32_bf16 v[118:121], v[158:161], v[174:177], v[118:121]
	v_mfma_f32_16x16x32_bf16 v[114:117], v[166:169], v[174:177], v[114:117]
	v_mfma_f32_16x16x32_bf16 v[102:105], v[158:161], v[182:185], v[102:105]
	v_mfma_f32_16x16x32_bf16 v[98:101], v[166:169], v[182:185], v[98:101]
	v_mfma_f32_16x16x32_bf16 v[86:89], v[158:161], v[190:193], v[86:89]
	v_mfma_f32_16x16x32_bf16 v[82:85], v[166:169], v[190:193], v[82:85]
	v_mfma_f32_16x16x32_bf16 v[70:73], v[158:161], v[198:201], v[70:73]
	v_mfma_f32_16x16x32_bf16 v[66:69], v[166:169], v[198:201], v[66:69]
	v_mfma_f32_16x16x32_bf16 v[118:121], v[162:165], v[178:181], v[118:121]
	v_mfma_f32_16x16x32_bf16 v[114:117], v[170:173], v[178:181], v[114:117]
	v_mfma_f32_16x16x32_bf16 v[102:105], v[162:165], v[186:189], v[102:105]
	v_mfma_f32_16x16x32_bf16 v[98:101], v[170:173], v[186:189], v[98:101]
	v_mfma_f32_16x16x32_bf16 v[86:89], v[162:165], v[194:197], v[86:89]
	v_mfma_f32_16x16x32_bf16 v[82:85], v[170:173], v[194:197], v[82:85]
	v_mfma_f32_16x16x32_bf16 v[70:73], v[162:165], v[202:205], v[70:73]
	v_mfma_f32_16x16x32_bf16 v[66:69], v[170:173], v[202:205], v[66:69]
	s_setprio 0
	s_barrier
; #define PG8_STAGE(bufoff, gbase, voff) do { const char* gb_ = (const char*)(gbase); asm volatile("" : "+s"(gb_)); _Pragma("unroll") for (int _i = 0; _i < 2; ++_i) { unsigned vo_ = (voff)[_i]; asm volatile("" : "+v"(vo_)); \
;         __builtin_amdgcn_global_load_lds((const unsigned*)(gb_ + vo_), (PG8_LAS unsigned*)(lds + (bufoff) + ldsw + _i * 8192), 16, 0, 0); } } while (0)
; #define PG8_LDA(dst, b, h) do { _Pragma("unroll") for (int m = 0; m < 4; ++m) _Pragma("unroll") for (int k = 0; k < 2; ++k) dst[m][k] = *(const PG8_LAS bf16x8*)(lds + PG8_SA(b, h) + aoff + m * 2048 + k * 1024); } while (0)
; #define PG8_LDB(dst, b, h) do { _Pragma("unroll") for (int n = 0; n < 2; ++n) _Pragma("unroll") for (int k = 0; k < 2; ++k) dst[n][k] = *(const PG8_LAS bf16x8*)(lds + PG8_SB(b, h) + boff + n * 2048 + k * 1024); } while (0)
; #define PG8_MMA(ai, bj, At, Bt) do { __builtin_amdgcn_s_setprio(1); _Pragma("unroll") for (int m = 0; m < 4; ++m) _Pragma("unroll") for (int n = 0; n < 2; ++n) _Pragma("unroll") for (int k = 0; k < 2; ++k) \
;         acc[ai][bj][m][n] = __builtin_amdgcn_mfma_f32_16x16x32_bf16(Bt[n][k], At[m][k], acc[ai][bj][m][n], 0, 0, 0); __builtin_amdgcn_s_setprio(0); } while (0)
; #define PG8_WAIT_V(n) asm volatile("s_waitcnt vmcnt(" #n ")" ::: "memory")
; #define PG8_BAR __builtin_amdgcn_s_barrier()
;     ...
;             if constexpr (SP2) {
;             PG8_LDB(B0, 0, 0); PG8_LDB(B1, 0, 1); PG8_SCHED; PG8_LDA(At, 0, 0); PG8_STAGE(PG8_SA(1, 1), a1 + hstep, voffA);
;             PG8_WAIT_V(8); PG8_WAIT_L(0); PG8_BAR; PG8_MMA(0, 0, At, B0); PG8_MMA(0, 1, At, B1); PG8_BAR; PG8_SCHED;
;             PG8_LDA(At, 0, 1); PG8_STAGE(PG8_SB(0, 0), b2, voffB); PG8_STAGE(PG8_SB(0, 1), b2 + hstepB, voffB); PG8_STAGE(PG8_SA(0, 0), a2, voffA);
;             PG8_WAIT_V(8); PG8_WAIT_L(0); PG8_BAR; PG8_MMA(1, 0, At, B0); PG8_MMA(1, 1, At, B1); PG8_BAR; PG8_SCHED;
;             PG8_LDB(B0, 1, 0); PG8_LDB(B1, 1, 1); PG8_SCHED; PG8_LDA(At, 1, 0); PG8_STAGE(PG8_SA(0, 1), a2 + hstep, voffA);
;             PG8_WAIT_V(8); PG8_WAIT_L(0); PG8_BAR; PG8_MMA(0, 0, At, B0); PG8_MMA(0, 1, At, B1); PG8_BAR; PG8_SCHED;
;             PG8_LDA(At, 1, 1); PG8_STAGE(PG8_SB(1, 0), b3, voffB); PG8_STAGE(PG8_SB(1, 1), b3 + hstepB, voffB); PG8_STAGE(PG8_SA(1, 0), a3, voffA);
;             PG8_WAIT_V(8); PG8_WAIT_L(0); PG8_BAR; PG8_MMA(1, 0, At, B0); PG8_MMA(1, 1, At, B1); PG8_BAR; PG8_SCHED;
	s_add_u32 s28, s26, 0x80
	s_addc_u32 s29, s27, 0
	v_mov_b32_e32 v206, v136
	s_add_i32 s46, s46, s1
	ds_read_b128 v[174:177], v141 offset:49152
	ds_read_b128 v[178:181], v141 offset:50176
	ds_read_b128 v[182:185], v141 offset:51200
	ds_read_b128 v[186:189], v141 offset:52224
	ds_read_b128 v[190:193], v141 offset:53248
	ds_read_b128 v[194:197], v141 offset:54272
	ds_read_b128 v[198:201], v141 offset:55296
	ds_read_b128 v[202:205], v141 offset:56320
	s_mov_b32 m0, s46
	s_nop 0
	global_load_lds_dwordx4 v206, s[28:29]
	v_mov_b32_e32 v206, v138
	s_add_i32 m0, s46, 0x2000
	s_add_u32 s26, s26, 0x40080
	global_load_lds_dwordx4 v206, s[28:29]
	s_addc_u32 s27, s27, 0
	v_mov_b32_e32 v206, v136
	s_add_i32 s28, s47, s1
	s_mov_b32 m0, s28
	s_nop 0
	global_load_lds_dwordx4 v206, s[26:27]
	v_mov_b32_e32 v206, v138
	s_add_i32 m0, s28, 0x2000
	s_nop 0
	global_load_lds_dwordx4 v206, s[26:27]
	v_mov_b32_e32 v206, v135
	s_mov_b32 m0, s38
	s_nop 0
	global_load_lds_dwordx4 v206, s[24:25]
	v_mov_b32_e32 v206, v137
	s_mov_b32 m0, s39
	s_nop 0
	global_load_lds_dwordx4 v206, s[24:25]
	s_waitcnt vmcnt(8)
	s_waitcnt lgkmcnt(0)
	s_barrier
	s_setprio 1
	s_waitcnt lgkmcnt(0)
	v_mfma_f32_16x16x32_bf16 v[62:65], v[142:145], v[174:177], v[62:65]
	v_mfma_f32_16x16x32_bf16 v[58:61], v[150:153], v[174:177], v[58:61]
	v_mfma_f32_16x16x32_bf16 v[46:49], v[142:145], v[182:185], v[46:49]
	v_mfma_f32_16x16x32_bf16 v[42:45], v[150:153], v[182:185], v[42:45]
	v_mfma_f32_16x16x32_bf16 v[30:33], v[142:145], v[190:193], v[30:33]
	v_mfma_f32_16x16x32_bf16 v[26:29], v[150:153], v[190:193], v[26:29]
	v_mfma_f32_16x16x32_bf16 v[14:17], v[142:145], v[198:201], v[14:17]
	v_mfma_f32_16x16x32_bf16 v[10:13], v[150:153], v[198:201], v[10:13]
	v_mfma_f32_16x16x32_bf16 v[62:65], v[146:149], v[178:181], v[62:65]
	v_mfma_f32_16x16x32_bf16 v[58:61], v[154:157], v[178:181], v[58:61]
	v_mfma_f32_16x16x32_bf16 v[46:49], v[146:149], v[186:189], v[46:49]
	v_mfma_f32_16x16x32_bf16 v[42:45], v[154:157], v[186:189], v[42:45]
	v_mfma_f32_16x16x32_bf16 v[30:33], v[146:149], v[194:197], v[30:33]
	v_mfma_f32_16x16x32_bf16 v[26:29], v[154:157], v[194:197], v[26:29]
	v_mfma_f32_16x16x32_bf16 v[14:17], v[146:149], v[202:205], v[14:17]
	v_mfma_f32_16x16x32_bf16 v[10:13], v[154:157], v[202:205], v[10:13]
	s_setprio 0
	s_setprio 1
	v_mfma_f32_16x16x32_bf16 v[54:57], v[158:161], v[174:177], v[54:57]
	v_mfma_f32_16x16x32_bf16 v[50:53], v[166:169], v[174:177], v[50:53]
	v_mfma_f32_16x16x32_bf16 v[38:41], v[158:161], v[182:185], v[38:41]
	v_mfma_f32_16x16x32_bf16 v[34:37], v[166:169], v[182:185], v[34:37]
	v_mfma_f32_16x16x32_bf16 v[22:25], v[158:161], v[190:193], v[22:25]
	v_mfma_f32_16x16x32_bf16 v[18:21], v[166:169], v[190:193], v[18:21]
	v_mfma_f32_16x16x32_bf16 v[6:9], v[158:161], v[198:201], v[6:9]
	v_mfma_f32_16x16x32_bf16 v[2:5], v[166:169], v[198:201], v[2:5]
	v_mfma_f32_16x16x32_bf16 v[54:57], v[162:165], v[178:181], v[54:57]
	v_mfma_f32_16x16x32_bf16 v[50:53], v[170:173], v[178:181], v[50:53]
	v_mfma_f32_16x16x32_bf16 v[38:41], v[162:165], v[186:189], v[38:41]
	v_mfma_f32_16x16x32_bf16 v[34:37], v[170:173], v[186:189], v[34:37]
	v_mfma_f32_16x16x32_bf16 v[22:25], v[162:165], v[194:197], v[22:25]
	v_mfma_f32_16x16x32_bf16 v[18:21], v[170:173], v[194:197], v[18:21]
	v_mfma_f32_16x16x32_bf16 v[6:9], v[162:165], v[202:205], v[6:9]
	v_mfma_f32_16x16x32_bf16 v[2:5], v[170:173], v[202:205], v[2:5]
	s_setprio 0
	s_barrier
	s_add_i32 s45, s45, 2
	s_add_u32 s22, s22, 0x100
	s_addc_u32 s23, s23, 0
	s_cmp_gt_u32 s45, 13
.LBB0_799:
	s_add_u32 s46, s14, s22
	s_addc_u32 s47, s15, s23
	s_add_u32 s24, s46, 0x100
	s_addc_u32 s25, s47, 0
	v_add_u32_e32 v154, s40, v140
	v_add_u32_e32 v170, s41, v140
	s_add_u32 s26, s12, s22
	ds_read_b128 v[142:145], v154
	ds_read_b128 v[146:149], v154 offset:1024
	ds_read_b128 v[150:153], v154 offset:2048
	ds_read_b128 v[154:157], v154 offset:3072
	ds_read_b128 v[158:161], v170
	ds_read_b128 v[162:165], v170 offset:1024
	ds_read_b128 v[166:169], v170 offset:2048
	ds_read_b128 v[170:173], v170 offset:3072
	s_addc_u32 s27, s13, s23
	s_add_u32 s26, s26, 0x100
	s_addc_u32 s27, s27, 0
	s_cmp_eq_u32 s45, 12
	s_cselect_b32 s28, s43, s24
	s_cselect_b32 s29, s19, s25
	s_cselect_b32 s26, s44, s26
	s_cselect_b32 s27, s17, s27
	s_add_u32 s24, s28, 0x80
	s_addc_u32 s25, s29, 0
	s_add_u32 s46, s46, 0x40080
	s_addc_u32 s47, s47, 0
	v_mov_b32_e32 v206, v135
	s_waitcnt lgkmcnt(7)
	ds_read_b128 v[174:177], v141
	ds_read_b128 v[178:181], v141 offset:1024
	ds_read_b128 v[182:185], v141 offset:2048
	ds_read_b128 v[186:189], v141 offset:3072
	ds_read_b128 v[190:193], v141 offset:4096
	ds_read_b128 v[194:197], v141 offset:5120
	ds_read_b128 v[198:201], v141 offset:6144
	ds_read_b128 v[202:205], v141 offset:7168
	s_add_i32 m0, s33, 0xc000
	s_nop 0
	global_load_lds_dwordx4 v206, s[46:47]
	v_mov_b32_e32 v206, v137
	s_add_i32 m0, s33, 0xe000
	s_nop 0
	global_load_lds_dwordx4 v206, s[46:47]
	s_waitcnt vmcnt(8)
	s_waitcnt lgkmcnt(0)
	s_barrier
; #define PG8_STAGE(bufoff, gbase, voff) do { const char* gb_ = (const char*)(gbase); asm volatile("" : "+s"(gb_)); _Pragma("unroll") for (int _i = 0; _i < 2; ++_i) { unsigned vo_ = (voff)[_i]; asm volatile("" : "+v"(vo_)); \
;         __builtin_amdgcn_global_load_lds((const unsigned*)(gb_ + vo_), (PG8_LAS unsigned*)(lds + (bufoff) + ldsw + _i * 8192), 16, 0, 0); } } while (0)
; #define PG8_LDA(dst, b, h) do { _Pragma("unroll") for (int m = 0; m < 4; ++m) _Pragma("unroll") for (int k = 0; k < 2; ++k) dst[m][k] = *(const PG8_LAS bf16x8*)(lds + PG8_SA(b, h) + aoff + m * 2048 + k * 1024); } while (0)
; #define PG8_LDB(dst, b, h) do { _Pragma("unroll") for (int n = 0; n < 2; ++n) _Pragma("unroll") for (int k = 0; k < 2; ++k) dst[n][k] = *(const PG8_LAS bf16x8*)(lds + PG8_SB(b, h) + boff + n * 2048 + k * 1024); } while (0)
; #define PG8_MMA(ai, bj, At, Bt) do { __builtin_amdgcn_s_setprio(1); _Pragma("unroll") for (int m = 0; m < 4; ++m) _Pragma("unroll") for (int n = 0; n < 2; ++n) _Pragma("unroll") for (int k = 0; k < 2; ++k) \
;         acc[ai][bj][m][n] = __builtin_amdgcn_mfma_f32_16x16x32_bf16(Bt[n][k], At[m][k], acc[ai][bj][m][n], 0, 0, 0); __builtin_amdgcn_s_setprio(0); } while (0)
; #define PG8_WAIT_V(n) asm volatile("s_waitcnt vmcnt(" #n ")" ::: "memory")
; #define PG8_BAR __builtin_amdgcn_s_barrier()
;     ...
;             if constexpr (SP2) {
;             PG8_LDB(B0, 0, 0); PG8_LDB(B1, 0, 1); PG8_SCHED; PG8_LDA(At, 0, 0); PG8_STAGE(PG8_SA(1, 1), a1 + hstep, voffA);
;             PG8_WAIT_V(8); PG8_WAIT_L(0); PG8_BAR; PG8_MMA(0, 0, At, B0); PG8_MMA(0, 1, At, B1); PG8_BAR; PG8_SCHED;
;             PG8_LDA(At, 0, 1); PG8_STAGE(PG8_SB(0, 0), b2, voffB); PG8_STAGE(PG8_SB(0, 1), b2 + hstepB, voffB); PG8_STAGE(PG8_SA(0, 0), a2, voffA);
;             PG8_WAIT_V(8); PG8_WAIT_L(0); PG8_BAR; PG8_MMA(1, 0, At, B0); PG8_MMA(1, 1, At, B1); PG8_BAR; PG8_SCHED;
;             PG8_LDB(B0, 1, 0); PG8_LDB(B1, 1, 1); PG8_SCHED; PG8_LDA(At, 1, 0); PG8_STAGE(PG8_SA(0, 1), a2 + hstep, voffA);
;             PG8_WAIT_V(8); PG8_WAIT_L(0); PG8_BAR; PG8_MMA(0, 0, At, B0); PG8_MMA(0, 1, At, B1); PG8_BAR; PG8_SCHED;
;             PG8_LDA(At, 1, 1); PG8_STAGE(PG8_SB(1, 0), b3, voffB); PG8_STAGE(PG8_SB(1, 1), b3 + hstepB, voffB); PG8_STAGE(PG8_SA(1, 0), a3, voffA);
;             PG8_WAIT_V(8); PG8_WAIT_L(0); PG8_BAR; PG8_MMA(1, 0, At, B0); PG8_MMA(1, 1, At, B1); PG8_BAR; PG8_SCHED;
	s_setprio 1
	s_waitcnt lgkmcnt(0)
	v_mfma_f32_16x16x32_bf16 v[126:129], v[142:145], v[174:177], v[126:129]
	v_mfma_f32_16x16x32_bf16 v[122:125], v[150:153], v[174:177], v[122:125]
	v_mfma_f32_16x16x32_bf16 v[110:113], v[142:145], v[182:185], v[110:113]
	v_mfma_f32_16x16x32_bf16 v[106:109], v[150:153], v[182:185], v[106:109]
	v_mfma_f32_16x16x32_bf16 v[94:97], v[142:145], v[190:193], v[94:97]
	v_mfma_f32_16x16x32_bf16 v[90:93], v[150:153], v[190:193], v[90:93]
	v_mfma_f32_16x16x32_bf16 v[78:81], v[142:145], v[198:201], v[78:81]
	v_mfma_f32_16x16x32_bf16 v[74:77], v[150:153], v[198:201], v[74:77]
	v_mfma_f32_16x16x32_bf16 v[126:129], v[146:149], v[178:181], v[126:129]
	v_mfma_f32_16x16x32_bf16 v[122:125], v[154:157], v[178:181], v[122:125]
	v_mfma_f32_16x16x32_bf16 v[110:113], v[146:149], v[186:189], v[110:113]
	v_mfma_f32_16x16x32_bf16 v[106:109], v[154:157], v[186:189], v[106:109]
	v_mfma_f32_16x16x32_bf16 v[94:97], v[146:149], v[194:197], v[94:97]
	v_mfma_f32_16x16x32_bf16 v[90:93], v[154:157], v[194:197], v[90:93]
	v_mfma_f32_16x16x32_bf16 v[78:81], v[146:149], v[202:205], v[78:81]
	v_mfma_f32_16x16x32_bf16 v[74:77], v[154:157], v[202:205], v[74:77]
	s_setprio 0
	s_setprio 1
	v_mfma_f32_16x16x32_bf16 v[118:121], v[158:161], v[174:177], v[118:121]
	v_mfma_f32_16x16x32_bf16 v[114:117], v[166:169], v[174:177], v[114:117]
	v_mfma_f32_16x16x32_bf16 v[102:105], v[158:161], v[182:185], v[102:105]
	v_mfma_f32_16x16x32_bf16 v[98:101], v[166:169], v[182:185], v[98:101]
	v_mfma_f32_16x16x32_bf16 v[86:89], v[158:161], v[190:193], v[86:89]
	v_mfma_f32_16x16x32_bf16 v[82:85], v[166:169], v[190:193], v[82:85]
	v_mfma_f32_16x16x32_bf16 v[70:73], v[158:161], v[198:201], v[70:73]
	v_mfma_f32_16x16x32_bf16 v[66:69], v[166:169], v[198:201], v[66:69]
	v_mfma_f32_16x16x32_bf16 v[118:121], v[162:165], v[178:181], v[118:121]
	v_mfma_f32_16x16x32_bf16 v[114:117], v[170:173], v[178:181], v[114:117]
	v_mfma_f32_16x16x32_bf16 v[102:105], v[162:165], v[186:189], v[102:105]
	v_mfma_f32_16x16x32_bf16 v[98:101], v[170:173], v[186:189], v[98:101]
	v_mfma_f32_16x16x32_bf16 v[86:89], v[162:165], v[194:197], v[86:89]
	v_mfma_f32_16x16x32_bf16 v[82:85], v[170:173], v[194:197], v[82:85]
	v_mfma_f32_16x16x32_bf16 v[70:73], v[162:165], v[202:205], v[70:73]
	v_mfma_f32_16x16x32_bf16 v[66:69], v[170:173], v[202:205], v[66:69]
	s_setprio 0
	s_barrier
	s_mov_b64 s[46:47], s[26:27]
	v_mov_b32_e32 v206, v136
	s_add_i32 s48, s40, s1
	ds_read_b128 v[174:177], v141 offset:16384
	ds_read_b128 v[178:181], v141 offset:17408
	ds_read_b128 v[182:185], v141 offset:18432
	ds_read_b128 v[186:189], v141 offset:19456
	ds_read_b128 v[190:193], v141 offset:20480
	ds_read_b128 v[194:197], v141 offset:21504
	ds_read_b128 v[198:201], v141 offset:22528
	ds_read_b128 v[202:205], v141 offset:23552
	s_mov_b32 m0, s48
	s_nop 0
	global_load_lds_dwordx4 v206, s[46:47]
	v_mov_b32_e32 v206, v138
	s_add_i32 m0, s48, 0x2000
	s_nop 0
	global_load_lds_dwordx4 v206, s[46:47]
	s_add_u32 s46, s26, 0x40000
	s_addc_u32 s47, s27, 0
	v_mov_b32_e32 v206, v136
	s_add_i32 s48, s41, s1
	s_mov_b32 m0, s48
	s_nop 0
	global_load_lds_dwordx4 v206, s[46:47]
	v_mov_b32_e32 v206, v138
	s_add_i32 m0, s48, 0x2000
	s_nop 0
	global_load_lds_dwordx4 v206, s[46:47]
	s_mov_b64 s[46:47], s[28:29]
	v_mov_b32_e32 v206, v135
	s_mov_b32 m0, s33
	s_nop 0
	global_load_lds_dwordx4 v206, s[46:47]
	v_mov_b32_e32 v206, v137
	s_mov_b32 m0, s34
	s_nop 0
	global_load_lds_dwordx4 v206, s[46:47]
	s_waitcnt vmcnt(8)
	s_waitcnt lgkmcnt(0)
	s_barrier
	s_setprio 1
	s_waitcnt lgkmcnt(0)
	v_mfma_f32_16x16x32_bf16 v[62:65], v[142:145], v[174:177], v[62:65]
	v_mfma_f32_16x16x32_bf16 v[58:61], v[150:153], v[174:177], v[58:61]
	v_mfma_f32_16x16x32_bf16 v[46:49], v[142:145], v[182:185], v[46:49]
	v_mfma_f32_16x16x32_bf16 v[42:45], v[150:153], v[182:185], v[42:45]
	v_mfma_f32_16x16x32_bf16 v[30:33], v[142:145], v[190:193], v[30:33]
	v_mfma_f32_16x16x32_bf16 v[26:29], v[150:153], v[190:193], v[26:29]
	v_mfma_f32_16x16x32_bf16 v[14:17], v[142:145], v[198:201], v[14:17]
	v_mfma_f32_16x16x32_bf16 v[10:13], v[150:153], v[198:201], v[10:13]
	v_mfma_f32_16x16x32_bf16 v[62:65], v[146:149], v[178:181], v[62:65]
	v_mfma_f32_16x16x32_bf16 v[58:61], v[154:157], v[178:181], v[58:61]
	v_mfma_f32_16x16x32_bf16 v[46:49], v[146:149], v[186:189], v[46:49]
	v_mfma_f32_16x16x32_bf16 v[42:45], v[154:157], v[186:189], v[42:45]
	v_mfma_f32_16x16x32_bf16 v[30:33], v[146:149], v[194:197], v[30:33]
	v_mfma_f32_16x16x32_bf16 v[26:29], v[154:157], v[194:197], v[26:29]
	v_mfma_f32_16x16x32_bf16 v[14:17], v[146:149], v[202:205], v[14:17]
	v_mfma_f32_16x16x32_bf16 v[10:13], v[154:157], v[202:205], v[10:13]
	s_setprio 0
	s_setprio 1
	v_mfma_f32_16x16x32_bf16 v[54:57], v[158:161], v[174:177], v[54:57]
	v_mfma_f32_16x16x32_bf16 v[50:53], v[166:169], v[174:177], v[50:53]
	v_mfma_f32_16x16x32_bf16 v[38:41], v[158:161], v[182:185], v[38:41]
	v_mfma_f32_16x16x32_bf16 v[34:37], v[166:169], v[182:185], v[34:37]
	v_mfma_f32_16x16x32_bf16 v[22:25], v[158:161], v[190:193], v[22:25]
	v_mfma_f32_16x16x32_bf16 v[18:21], v[166:169], v[190:193], v[18:21]
	v_mfma_f32_16x16x32_bf16 v[6:9], v[158:161], v[198:201], v[6:9]
	v_mfma_f32_16x16x32_bf16 v[2:5], v[166:169], v[198:201], v[2:5]
	v_mfma_f32_16x16x32_bf16 v[54:57], v[162:165], v[178:181], v[54:57]
	v_mfma_f32_16x16x32_bf16 v[50:53], v[170:173], v[178:181], v[50:53]
	v_mfma_f32_16x16x32_bf16 v[38:41], v[162:165], v[186:189], v[38:41]
	v_mfma_f32_16x16x32_bf16 v[34:37], v[170:173], v[186:189], v[34:37]
	v_mfma_f32_16x16x32_bf16 v[22:25], v[162:165], v[194:197], v[22:25]
	v_mfma_f32_16x16x32_bf16 v[18:21], v[170:173], v[194:197], v[18:21]
	v_mfma_f32_16x16x32_bf16 v[6:9], v[162:165], v[202:205], v[6:9]
	v_mfma_f32_16x16x32_bf16 v[2:5], v[170:173], v[202:205], v[2:5]
	s_setprio 0
	s_barrier
; #define PG8_STAGE(bufoff, gbase, voff) do { const char* gb_ = (const char*)(gbase); asm volatile("" : "+s"(gb_)); _Pragma("unroll") for (int _i = 0; _i < 2; ++_i) { unsigned vo_ = (voff)[_i]; asm volatile("" : "+v"(vo_)); \
;         __builtin_amdgcn_global_load_lds((const unsigned*)(gb_ + vo_), (PG8_LAS unsigned*)(lds + (bufoff) + ldsw + _i * 8192), 16, 0, 0); } } while (0)
; #define PG8_LDA(dst, b, h) do { _Pragma("unroll") for (int m = 0; m < 4; ++m) _Pragma("unroll") for (int k = 0; k < 2; ++k) dst[m][k] = *(const PG8_LAS bf16x8*)(lds + PG8_SA(b, h) + aoff + m * 2048 + k * 1024); } while (0)
; #define PG8_LDB(dst, b, h) do { _Pragma("unroll") for (int n = 0; n < 2; ++n) _Pragma("unroll") for (int k = 0; k < 2; ++k) dst[n][k] = *(const PG8_LAS bf16x8*)(lds + PG8_SB(b, h) + boff + n * 2048 + k * 1024); } while (0)
; #define PG8_MMA(ai, bj, At, Bt) do { __builtin_amdgcn_s_setprio(1); _Pragma("unroll") for (int m = 0; m < 4; ++m) _Pragma("unroll") for (int n = 0; n < 2; ++n) _Pragma("unroll") for (int k = 0; k < 2; ++k) \
;         acc[ai][bj][m][n] = __builtin_amdgcn_mfma_f32_16x16x32_bf16(Bt[n][k], At[m][k], acc[ai][bj][m][n], 0, 0, 0); __builtin_amdgcn_s_setprio(0); } while (0)
; #define PG8_WAIT_V(n) asm volatile("s_waitcnt vmcnt(" #n ")" ::: "memory")
; #define PG8_BAR __builtin_amdgcn_s_barrier()
;     ...
;             if constexpr (SP2) {
;             PG8_LDB(B0, 0, 0); PG8_LDB(B1, 0, 1); PG8_SCHED; PG8_LDA(At, 0, 0); PG8_STAGE(PG8_SA(1, 1), a1 + hstep, voffA);
;             PG8_WAIT_V(8); PG8_WAIT_L(0); PG8_BAR; PG8_MMA(0, 0, At, B0); PG8_MMA(0, 1, At, B1); PG8_BAR; PG8_SCHED;
;             PG8_LDA(At, 0, 1); PG8_STAGE(PG8_SB(0, 0), b2, voffB); PG8_STAGE(PG8_SB(0, 1), b2 + hstepB, voffB); PG8_STAGE(PG8_SA(0, 0), a2, voffA);
;             PG8_WAIT_V(8); PG8_WAIT_L(0); PG8_BAR; PG8_MMA(1, 0, At, B0); PG8_MMA(1, 1, At, B1); PG8_BAR; PG8_SCHED;
;             PG8_LDB(B0, 1, 0); PG8_LDB(B1, 1, 1); PG8_SCHED; PG8_LDA(At, 1, 0); PG8_STAGE(PG8_SA(0, 1), a2 + hstep, voffA);
;             PG8_WAIT_V(8); PG8_WAIT_L(0); PG8_BAR; PG8_MMA(0, 0, At, B0); PG8_MMA(0, 1, At, B1); PG8_BAR; PG8_SCHED;
;             PG8_LDA(At, 1, 1); PG8_STAGE(PG8_SB(1, 0), b3, voffB); PG8_STAGE(PG8_SB(1, 1), b3 + hstepB, voffB); PG8_STAGE(PG8_SA(1, 0), a3, voffA);
;             PG8_WAIT_V(8); PG8_WAIT_L(0); PG8_BAR; PG8_MMA(1, 0, At, B0); PG8_MMA(1, 1, At, B1); PG8_BAR; PG8_SCHED;
	s_add_i32 s46, 0, 0x18000
	s_add_i32 s47, 0, 0x1c000
	v_add_u32_e32 v154, s46, v140
	v_add_u32_e32 v170, s47, v140
	ds_read_b128 v[142:145], v154
	ds_read_b128 v[146:149], v154 offset:1024
	ds_read_b128 v[150:153], v154 offset:2048
	ds_read_b128 v[154:157], v154 offset:3072
	ds_read_b128 v[158:161], v170
	ds_read_b128 v[162:165], v170 offset:1024
	ds_read_b128 v[166:169], v170 offset:2048
	ds_read_b128 v[170:173], v170 offset:3072
	s_add_u32 s28, s28, 0x40000
	s_addc_u32 s29, s29, 0
	v_mov_b32_e32 v206, v135
	s_mov_b32 m0, s35
	ds_read_b128 v[174:177], v141 offset:32768
	ds_read_b128 v[178:181], v141 offset:33792
	ds_read_b128 v[182:185], v141 offset:34816
	ds_read_b128 v[186:189], v141 offset:35840
	ds_read_b128 v[190:193], v141 offset:36864
	ds_read_b128 v[194:197], v141 offset:37888
	ds_read_b128 v[198:201], v141 offset:38912
	ds_read_b128 v[202:205], v141 offset:39936
	s_nop 0
	global_load_lds_dwordx4 v206, s[28:29]
	v_mov_b32_e32 v206, v137
	s_mov_b32 m0, s36
	s_nop 0
	global_load_lds_dwordx4 v206, s[28:29]
	s_waitcnt vmcnt(8)
	s_waitcnt lgkmcnt(0)
	s_barrier
	s_setprio 1
	s_waitcnt lgkmcnt(0)
	v_mfma_f32_16x16x32_bf16 v[126:129], v[142:145], v[174:177], v[126:129]
	v_mfma_f32_16x16x32_bf16 v[122:125], v[150:153], v[174:177], v[122:125]
	v_mfma_f32_16x16x32_bf16 v[110:113], v[142:145], v[182:185], v[110:113]
	v_mfma_f32_16x16x32_bf16 v[106:109], v[150:153], v[182:185], v[106:109]
	v_mfma_f32_16x16x32_bf16 v[94:97], v[142:145], v[190:193], v[94:97]
	v_mfma_f32_16x16x32_bf16 v[90:93], v[150:153], v[190:193], v[90:93]
	v_mfma_f32_16x16x32_bf16 v[78:81], v[142:145], v[198:201], v[78:81]
	v_mfma_f32_16x16x32_bf16 v[74:77], v[150:153], v[198:201], v[74:77]
	v_mfma_f32_16x16x32_bf16 v[126:129], v[146:149], v[178:181], v[126:129]
	v_mfma_f32_16x16x32_bf16 v[122:125], v[154:157], v[178:181], v[122:125]
	v_mfma_f32_16x16x32_bf16 v[110:113], v[146:149], v[186:189], v[110:113]
	v_mfma_f32_16x16x32_bf16 v[106:109], v[154:157], v[186:189], v[106:109]
	v_mfma_f32_16x16x32_bf16 v[94:97], v[146:149], v[194:197], v[94:97]
	v_mfma_f32_16x16x32_bf16 v[90:93], v[154:157], v[194:197], v[90:93]
	v_mfma_f32_16x16x32_bf16 v[78:81], v[146:149], v[202:205], v[78:81]
	v_mfma_f32_16x16x32_bf16 v[74:77], v[154:157], v[202:205], v[74:77]
	s_setprio 0
	s_setprio 1
	v_mfma_f32_16x16x32_bf16 v[118:121], v[158:161], v[174:177], v[118:121]
	v_mfma_f32_16x16x32_bf16 v[114:117], v[166:169], v[174:177], v[114:117]
	v_mfma_f32_16x16x32_bf16 v[102:105], v[158:161], v[182:185], v[102:105]
	v_mfma_f32_16x16x32_bf16 v[98:101], v[166:169], v[182:185], v[98:101]
	v_mfma_f32_16x16x32_bf16 v[86:89], v[158:161], v[190:193], v[86:89]
	v_mfma_f32_16x16x32_bf16 v[82:85], v[166:169], v[190:193], v[82:85]
	v_mfma_f32_16x16x32_bf16 v[70:73], v[158:161], v[198:201], v[70:73]
	v_mfma_f32_16x16x32_bf16 v[66:69], v[166:169], v[198:201], v[66:69]
	v_mfma_f32_16x16x32_bf16 v[118:121], v[162:165], v[178:181], v[118:121]
	v_mfma_f32_16x16x32_bf16 v[114:117], v[170:173], v[178:181], v[114:117]
	v_mfma_f32_16x16x32_bf16 v[102:105], v[162:165], v[186:189], v[102:105]
	v_mfma_f32_16x16x32_bf16 v[98:101], v[170:173], v[186:189], v[98:101]
	v_mfma_f32_16x16x32_bf16 v[86:89], v[162:165], v[194:197], v[86:89]
	v_mfma_f32_16x16x32_bf16 v[82:85], v[170:173], v[194:197], v[82:85]
	v_mfma_f32_16x16x32_bf16 v[70:73], v[162:165], v[202:205], v[70:73]
	v_mfma_f32_16x16x32_bf16 v[66:69], v[170:173], v[202:205], v[66:69]
	s_setprio 0
	s_barrier
; #define PG8_STAGE(bufoff, gbase, voff) do { const char* gb_ = (const char*)(gbase); asm volatile("" : "+s"(gb_)); _Pragma("unroll") for (int _i = 0; _i < 2; ++_i) { unsigned vo_ = (voff)[_i]; asm volatile("" : "+v"(vo_)); \
;         __builtin_amdgcn_global_load_lds((const unsigned*)(gb_ + vo_), (PG8_LAS unsigned*)(lds + (bufoff) + ldsw + _i * 8192), 16, 0, 0); } } while (0)
; #define PG8_LDA(dst, b, h) do { _Pragma("unroll") for (int m = 0; m < 4; ++m) _Pragma("unroll") for (int k = 0; k < 2; ++k) dst[m][k] = *(const PG8_LAS bf16x8*)(lds + PG8_SA(b, h) + aoff + m * 2048 + k * 1024); } while (0)
; #define PG8_LDB(dst, b, h) do { _Pragma("unroll") for (int n = 0; n < 2; ++n) _Pragma("unroll") for (int k = 0; k < 2; ++k) dst[n][k] = *(const PG8_LAS bf16x8*)(lds + PG8_SB(b, h) + boff + n * 2048 + k * 1024); } while (0)
; #define PG8_WAIT_V(n) asm volatile("s_waitcnt vmcnt(" #n ")" ::: "memory")
;     ...
;             if constexpr (SP2) {
;             PG8_LDB(B0, 0, 0); PG8_LDB(B1, 0, 1); PG8_SCHED; PG8_LDA(At, 0, 0); PG8_STAGE(PG8_SA(1, 1), a1 + hstep, voffA);
;             PG8_WAIT_V(8); PG8_WAIT_L(0); PG8_BAR; PG8_MMA(0, 0, At, B0); PG8_MMA(0, 1, At, B1); PG8_BAR; PG8_SCHED;
;             PG8_LDA(At, 0, 1); PG8_STAGE(PG8_SB(0, 0), b2, voffB); PG8_STAGE(PG8_SB(0, 1), b2 + hstepB, voffB); PG8_STAGE(PG8_SA(0, 0), a2, voffA);
;             PG8_WAIT_V(8); PG8_WAIT_L(0); PG8_BAR; PG8_MMA(1, 0, At, B0); PG8_MMA(1, 1, At, B1); PG8_BAR; PG8_SCHED;
;             PG8_LDB(B0, 1, 0); PG8_LDB(B1, 1, 1); PG8_SCHED; PG8_LDA(At, 1, 0); PG8_STAGE(PG8_SA(0, 1), a2 + hstep, voffA);
;             PG8_WAIT_V(8); PG8_WAIT_L(0); PG8_BAR; PG8_MMA(0, 0, At, B0); PG8_MMA(0, 1, At, B1); PG8_BAR; PG8_SCHED;
;             PG8_LDA(At, 1, 1); PG8_STAGE(PG8_SB(1, 0), b3, voffB); PG8_STAGE(PG8_SB(1, 1), b3 + hstepB, voffB); PG8_STAGE(PG8_SA(1, 0), a3, voffA);
;             PG8_WAIT_V(8); PG8_WAIT_L(0); PG8_BAR; PG8_MMA(1, 0, At, B0); PG8_MMA(1, 1, At, B1); PG8_BAR; PG8_SCHED;
;     ...
;         if (!has_next) break;
;         if constexpr (!Epi::KEEP_ACC) {
; #pragma unroll
;         for (int a = 0; a < 2; ++a)
; #pragma unroll
;             for (int b = 0; b < 2; ++b)
; #pragma unroll
;                 for (int m = 0; m < 4; ++m)
; #pragma unroll
;                     for (int n = 0; n < 2; ++n) acc[a][b][m][n] = (f32x4){0.f, 0.f, 0.f, 0.f};
;         }
;         cur = nxt; cA = nA; cB = nB; ++ui;
	s_add_u32 s28, s26, 0x80
	s_addc_u32 s29, s27, 0
	v_mov_b32_e32 v206, v136
	s_add_i32 s46, s46, s1
	ds_read_b128 v[174:177], v141 offset:49152
	ds_read_b128 v[178:181], v141 offset:50176
	ds_read_b128 v[182:185], v141 offset:51200
	ds_read_b128 v[186:189], v141 offset:52224
	ds_read_b128 v[190:193], v141 offset:53248
	ds_read_b128 v[194:197], v141 offset:54272
	ds_read_b128 v[198:201], v141 offset:55296
	ds_read_b128 v[202:205], v141 offset:56320
	s_mov_b32 m0, s46
	s_nop 0
	global_load_lds_dwordx4 v206, s[28:29]
	v_mov_b32_e32 v206, v138
	s_add_i32 m0, s46, 0x2000
	s_add_u32 s26, s26, 0x40080
	global_load_lds_dwordx4 v206, s[28:29]
	s_addc_u32 s27, s27, 0
	v_mov_b32_e32 v206, v136
	s_add_i32 s28, s47, s1
	s_mov_b32 m0, s28
	s_nop 0
	global_load_lds_dwordx4 v206, s[26:27]
	v_mov_b32_e32 v206, v138
	s_add_i32 m0, s28, 0x2000
	s_nop 0
	global_load_lds_dwordx4 v206, s[26:27]
	v_mov_b32_e32 v206, v135
	s_mov_b32 m0, s38
	s_nop 0
	global_load_lds_dwordx4 v206, s[24:25]
	v_mov_b32_e32 v206, v137
	s_mov_b32 m0, s39
	s_nop 0
	global_load_lds_dwordx4 v206, s[24:25]
	s_waitcnt vmcnt(8)
	s_waitcnt lgkmcnt(0)
	s_barrier
	s_setprio 1
	s_waitcnt lgkmcnt(0)
	v_mfma_f32_16x16x32_bf16 v[62:65], v[142:145], v[174:177], v[62:65]
	v_mfma_f32_16x16x32_bf16 v[58:61], v[150:153], v[174:177], v[58:61]
	v_mfma_f32_16x16x32_bf16 v[46:49], v[142:145], v[182:185], v[46:49]
	v_mfma_f32_16x16x32_bf16 v[42:45], v[150:153], v[182:185], v[42:45]
	v_mfma_f32_16x16x32_bf16 v[30:33], v[142:145], v[190:193], v[30:33]
	v_mfma_f32_16x16x32_bf16 v[26:29], v[150:153], v[190:193], v[26:29]
	v_mfma_f32_16x16x32_bf16 v[14:17], v[142:145], v[198:201], v[14:17]
	v_mfma_f32_16x16x32_bf16 v[10:13], v[150:153], v[198:201], v[10:13]
	v_mfma_f32_16x16x32_bf16 v[62:65], v[146:149], v[178:181], v[62:65]
	v_mfma_f32_16x16x32_bf16 v[58:61], v[154:157], v[178:181], v[58:61]
	v_mfma_f32_16x16x32_bf16 v[46:49], v[146:149], v[186:189], v[46:49]
	v_mfma_f32_16x16x32_bf16 v[42:45], v[154:157], v[186:189], v[42:45]
	v_mfma_f32_16x16x32_bf16 v[30:33], v[146:149], v[194:197], v[30:33]
	v_mfma_f32_16x16x32_bf16 v[26:29], v[154:157], v[194:197], v[26:29]
	v_mfma_f32_16x16x32_bf16 v[14:17], v[146:149], v[202:205], v[14:17]
	v_mfma_f32_16x16x32_bf16 v[10:13], v[154:157], v[202:205], v[10:13]
	s_setprio 0
	s_setprio 1
	v_mfma_f32_16x16x32_bf16 v[54:57], v[158:161], v[174:177], v[54:57]
	v_mfma_f32_16x16x32_bf16 v[50:53], v[166:169], v[174:177], v[50:53]
	v_mfma_f32_16x16x32_bf16 v[38:41], v[158:161], v[182:185], v[38:41]
	v_mfma_f32_16x16x32_bf16 v[34:37], v[166:169], v[182:185], v[34:37]
	v_mfma_f32_16x16x32_bf16 v[22:25], v[158:161], v[190:193], v[22:25]
	v_mfma_f32_16x16x32_bf16 v[18:21], v[166:169], v[190:193], v[18:21]
	v_mfma_f32_16x16x32_bf16 v[6:9], v[158:161], v[198:201], v[6:9]
	v_mfma_f32_16x16x32_bf16 v[2:5], v[166:169], v[198:201], v[2:5]
	v_mfma_f32_16x16x32_bf16 v[54:57], v[162:165], v[178:181], v[54:57]
	v_mfma_f32_16x16x32_bf16 v[50:53], v[170:173], v[178:181], v[50:53]
	v_mfma_f32_16x16x32_bf16 v[38:41], v[162:165], v[186:189], v[38:41]
	v_mfma_f32_16x16x32_bf16 v[34:37], v[170:173], v[186:189], v[34:37]
	v_mfma_f32_16x16x32_bf16 v[22:25], v[162:165], v[194:197], v[22:25]
	v_mfma_f32_16x16x32_bf16 v[18:21], v[170:173], v[194:197], v[18:21]
	v_mfma_f32_16x16x32_bf16 v[6:9], v[162:165], v[202:205], v[6:9]
	v_mfma_f32_16x16x32_bf16 v[2:5], v[170:173], v[202:205], v[2:5]
	s_setprio 0
	s_barrier
	s_add_i32 s45, s45, 2
	s_add_u32 s22, s22, 0x100
	s_addc_u32 s23, s23, 0
	s_cmp_gt_u32 s45, 13
	s_cbranch_scc0 .LBB0_799
	s_andn2_b64 vcc, exec, s[4:5]
	s_cbranch_vccnz .LBB0_791
	s_mov_b32 s0, s16
	s_mov_b32 s10, s18
	s_mov_b64 s[12:13], s[20:21]
	s_mov_b64 s[14:15], s[2:3]
	s_mov_b32 s37, s42
	s_branch .LBB0_791

;     __device__ __forceinline__ bool next(int i, Unit& u) const { const long L = (long)i * G + c; if (L >= (long)nM * nN) return false; static_tile((int)L, nM, nN, u.pm, u.pn); u.br = 0; return true; }
; #define PG8_WAIT_V(n) asm volatile("s_waitcnt vmcnt(" #n ")" ::: "memory")
;     ...
;     for (;;) {
;         const bool has_next = S.next(ui + 1, nxt);
;         if (GP) gpU = __builtin_amdgcn_s_memrealtime();
;         const char* nA = has_next ? S.a_ptr(nxt) : cA; const char* nB = has_next ? S.b_ptr(nxt) : cB;
;         for (int t = 0; t < nt; t += 2) {
;             const bool last = (t == nt - 2);
;             if (GP && t == 2) gp1 = __builtin_amdgcn_s_memrealtime();
;             const char* a1 = cA + (size_t)(t + 1) * kstep;
;             const char* a2 = last ? nA : cA + (size_t)(t + 2) * kstep; const char* b2 = last ? nB : cB + (size_t)(t + 2) * kstep;
;             const char* a3 = a2 + kstep; const char* b3 = b2 + kstep;
;             if (last && has_next) S.a_ready(nxt);
;             if constexpr (SP2) {
;             PG8_LDB(B0, 0, 0); PG8_LDB(B1, 0, 1); PG8_SCHED; PG8_LDA(At, 0, 0); PG8_STAGE(PG8_SA(1, 1), a1 + hstep, voffA);
;             PG8_WAIT_V(8); PG8_WAIT_L(0); PG8_BAR; PG8_MMA(0, 0, At, B0); PG8_MMA(0, 1, At, B1); PG8_BAR; PG8_SCHED;
;             PG8_LDA(At, 0, 1); PG8_STAGE(PG8_SB(0, 0), b2, voffB); PG8_STAGE(PG8_SB(0, 1), b2 + hstepB, voffB); PG8_STAGE(PG8_SA(0, 0), a2, voffA);
;             PG8_WAIT_V(8); PG8_WAIT_L(0); PG8_BAR; PG8_MMA(1, 0, At, B0); PG8_MMA(1, 1, At, B1); PG8_BAR; PG8_SCHED;
;             PG8_LDB(B0, 1, 0); PG8_LDB(B1, 1, 1); PG8_SCHED; PG8_LDA(At, 1, 0); PG8_STAGE(PG8_SA(0, 1), a2 + hstep, voffA);
;             PG8_WAIT_V(8); PG8_WAIT_L(0); PG8_BAR; PG8_MMA(0, 0, At, B0); PG8_MMA(0, 1, At, B1); PG8_BAR; PG8_SCHED;
;             PG8_LDA(At, 1, 1); PG8_STAGE(PG8_SB(1, 0), b3, voffB); PG8_STAGE(PG8_SB(1, 1), b3 + hstepB, voffB); PG8_STAGE(PG8_SA(1, 0), a3, voffA);
;             PG8_WAIT_V(8); PG8_WAIT_L(0); PG8_BAR; PG8_MMA(1, 0, At, B0); PG8_MMA(1, 1, At, B1); PG8_BAR; PG8_SCHED;
;     ...
;         if constexpr (!Epi::KEEP_ACC) {
; #pragma unroll
;         for (int a = 0; a < 2; ++a)
; #pragma unroll
;             for (int b = 0; b < 2; ++b)
; #pragma unroll
;                 for (int m = 0; m < 4; ++m)
; #pragma unroll
;                     for (int n = 0; n < 2; ++n) acc[a][b][m][n] = (f32x4){0.f, 0.f, 0.f, 0.f};
;         }
.LBB0_894:
	s_ashr_i32 s11, s10, 31
	s_lshl_b64 s[12:13], s[10:11], 19
	v_readlane_b32 s14, v247, 49
	v_readlane_b32 s15, v247, 50
	s_add_u32 s12, s14, s12
	s_addc_u32 s13, s15, s13
	s_and_b64 s[14:15], s[4:5], exec
	s_cselect_b32 s11, s13, s19
	s_cselect_b32 s50, s12, s18
	s_ashr_i32 s7, s6, 31
	s_lshl_b64 s[14:15], s[6:7], 19
	s_add_u32 s14, s58, s14
	s_addc_u32 s15, s59, s15
	s_and_b64 s[22:23], s[4:5], exec
	s_cselect_b32 s7, s15, s21
	s_cselect_b32 s51, s14, s20
	s_add_u32 s52, s20, 0x100
	s_addc_u32 s53, s21, 0
	s_mov_b32 s54, -2
	ds_read_b128 v[146:149], v142
	ds_read_b128 v[150:153], v142 offset:1024
	ds_read_b128 v[154:157], v142 offset:2048
	ds_read_b128 v[158:161], v142 offset:3072
	ds_read_b128 v[162:165], v143
	ds_read_b128 v[166:169], v143 offset:1024
	ds_read_b128 v[170:173], v143 offset:2048
	s_waitcnt lgkmcnt(6)
	ds_read_b128 v[174:177], v143 offset:3072
	s_add_u32 s20, s18, 0x100
	s_addc_u32 s21, s19, 0
	s_cmp_eq_u32 s54, 12
	s_cselect_b32 s26, s50, s20
	s_cselect_b32 s27, s11, s21
	s_cselect_b32 s24, s51, s52
	s_cselect_b32 s25, s7, s53
	s_add_u32 s22, s26, 0x80
	s_addc_u32 s23, s27, 0
	s_add_u32 s18, s18, 0x40080
	s_addc_u32 s19, s19, 0
	v_mov_b32_e32 v136, v1
	ds_read_b128 v[178:181], v144
	ds_read_b128 v[182:185], v144 offset:1024
	ds_read_b128 v[186:189], v144 offset:2048
	ds_read_b128 v[190:193], v144 offset:3072
	ds_read_b128 v[194:197], v144 offset:4096
	ds_read_b128 v[198:201], v144 offset:5120
	ds_read_b128 v[202:205], v144 offset:6144
	ds_read_b128 v[206:209], v144 offset:7168
	s_add_i32 m0, s17, 0xc000
	s_nop 0
	global_load_lds_dwordx4 v136, s[18:19]
	v_mov_b32_e32 v136, v139
	s_add_i32 m0, s17, 0xe000
	s_nop 0
	global_load_lds_dwordx4 v136, s[18:19]
	s_waitcnt vmcnt(8)
	s_waitcnt lgkmcnt(0)
	s_barrier
	s_setprio 1
	s_waitcnt lgkmcnt(0)
	v_mfma_f32_16x16x32_bf16 v[126:129], v[146:149], v[178:181], 0
	v_mfma_f32_16x16x32_bf16 v[122:125], v[154:157], v[178:181], 0
	v_mfma_f32_16x16x32_bf16 v[114:117], v[146:149], v[186:189], 0
	v_mfma_f32_16x16x32_bf16 v[106:109], v[154:157], v[186:189], 0
	v_mfma_f32_16x16x32_bf16 v[98:101], v[146:149], v[194:197], 0
	v_mfma_f32_16x16x32_bf16 v[90:93], v[154:157], v[194:197], 0
	v_mfma_f32_16x16x32_bf16 v[82:85], v[146:149], v[202:205], 0
	v_mfma_f32_16x16x32_bf16 v[74:77], v[154:157], v[202:205], 0
	v_mfma_f32_16x16x32_bf16 v[126:129], v[150:153], v[182:185], v[126:129]
	v_mfma_f32_16x16x32_bf16 v[122:125], v[158:161], v[182:185], v[122:125]
	v_mfma_f32_16x16x32_bf16 v[114:117], v[150:153], v[190:193], v[114:117]
	v_mfma_f32_16x16x32_bf16 v[106:109], v[158:161], v[190:193], v[106:109]
	v_mfma_f32_16x16x32_bf16 v[98:101], v[150:153], v[198:201], v[98:101]
	v_mfma_f32_16x16x32_bf16 v[90:93], v[158:161], v[198:201], v[90:93]
	v_mfma_f32_16x16x32_bf16 v[82:85], v[150:153], v[206:209], v[82:85]
	v_mfma_f32_16x16x32_bf16 v[74:77], v[158:161], v[206:209], v[74:77]
	s_setprio 0
	s_setprio 1
	v_mfma_f32_16x16x32_bf16 v[118:121], v[162:165], v[178:181], 0
	v_mfma_f32_16x16x32_bf16 v[110:113], v[170:173], v[178:181], 0
	v_mfma_f32_16x16x32_bf16 v[102:105], v[162:165], v[186:189], 0
	v_mfma_f32_16x16x32_bf16 v[94:97], v[170:173], v[186:189], 0
	v_mfma_f32_16x16x32_bf16 v[86:89], v[162:165], v[194:197], 0
	v_mfma_f32_16x16x32_bf16 v[78:81], v[170:173], v[194:197], 0
	v_mfma_f32_16x16x32_bf16 v[70:73], v[162:165], v[202:205], 0
	v_mfma_f32_16x16x32_bf16 v[66:69], v[170:173], v[202:205], 0
	v_mfma_f32_16x16x32_bf16 v[118:121], v[166:169], v[182:185], v[118:121]
	v_mfma_f32_16x16x32_bf16 v[110:113], v[174:177], v[182:185], v[110:113]
	v_mfma_f32_16x16x32_bf16 v[102:105], v[166:169], v[190:193], v[102:105]
	v_mfma_f32_16x16x32_bf16 v[94:97], v[174:177], v[190:193], v[94:97]
	v_mfma_f32_16x16x32_bf16 v[86:89], v[166:169], v[198:201], v[86:89]
	v_mfma_f32_16x16x32_bf16 v[78:81], v[174:177], v[198:201], v[78:81]
	v_mfma_f32_16x16x32_bf16 v[70:73], v[166:169], v[206:209], v[70:73]
	v_mfma_f32_16x16x32_bf16 v[66:69], v[174:177], v[206:209], v[66:69]
	s_setprio 0
	s_barrier
	s_mov_b64 s[18:19], s[24:25]
	v_mov_b32_e32 v136, v138
	s_add_i32 s55, s39, s29
	ds_read_b128 v[178:181], v144 offset:16384
	ds_read_b128 v[182:185], v144 offset:17408
	ds_read_b128 v[186:189], v144 offset:18432
	ds_read_b128 v[190:193], v144 offset:19456
	ds_read_b128 v[194:197], v144 offset:20480
	ds_read_b128 v[198:201], v144 offset:21504
	ds_read_b128 v[202:205], v144 offset:22528
	ds_read_b128 v[206:209], v144 offset:23552
	s_mov_b32 m0, s55
	s_nop 0
	global_load_lds_dwordx4 v136, s[18:19]
	v_mov_b32_e32 v136, v140
	s_add_i32 m0, s55, 0x2000
	s_nop 0
	global_load_lds_dwordx4 v136, s[18:19]
	s_add_u32 s18, s24, 0x10000
	s_addc_u32 s19, s25, 0
	v_mov_b32_e32 v136, v138
	s_add_i32 s55, s40, s29
	s_mov_b32 m0, s55
	s_nop 0
	global_load_lds_dwordx4 v136, s[18:19]
	v_mov_b32_e32 v136, v140
	s_add_i32 m0, s55, 0x2000
	s_nop 0
	global_load_lds_dwordx4 v136, s[18:19]
	s_mov_b64 s[18:19], s[26:27]
	v_mov_b32_e32 v136, v1
	s_mov_b32 m0, s17
	s_nop 0
	global_load_lds_dwordx4 v136, s[18:19]
	v_mov_b32_e32 v136, v139
	s_mov_b32 m0, s30
	s_nop 0
	global_load_lds_dwordx4 v136, s[18:19]
	s_waitcnt vmcnt(8)
	s_waitcnt lgkmcnt(0)
	s_barrier
; #define PG8_STAGE(bufoff, gbase, voff) do { const char* gb_ = (const char*)(gbase); asm volatile("" : "+s"(gb_)); _Pragma("unroll") for (int _i = 0; _i < 2; ++_i) { unsigned vo_ = (voff)[_i]; asm volatile("" : "+v"(vo_)); \
;         __builtin_amdgcn_global_load_lds((const unsigned*)(gb_ + vo_), (PG8_LAS unsigned*)(lds + (bufoff) + ldsw + _i * 8192), 16, 0, 0); } } while (0)
; #define PG8_LDA(dst, b, h) do { _Pragma("unroll") for (int m = 0; m < 4; ++m) _Pragma("unroll") for (int k = 0; k < 2; ++k) dst[m][k] = *(const PG8_LAS bf16x8*)(lds + PG8_SA(b, h) + aoff + m * 2048 + k * 1024); } while (0)
; #define PG8_LDB(dst, b, h) do { _Pragma("unroll") for (int n = 0; n < 2; ++n) _Pragma("unroll") for (int k = 0; k < 2; ++k) dst[n][k] = *(const PG8_LAS bf16x8*)(lds + PG8_SB(b, h) + boff + n * 2048 + k * 1024); } while (0)
; #define PG8_MMA(ai, bj, At, Bt) do { __builtin_amdgcn_s_setprio(1); _Pragma("unroll") for (int m = 0; m < 4; ++m) _Pragma("unroll") for (int n = 0; n < 2; ++n) _Pragma("unroll") for (int k = 0; k < 2; ++k) \
;         acc[ai][bj][m][n] = __builtin_amdgcn_mfma_f32_16x16x32_bf16(Bt[n][k], At[m][k], acc[ai][bj][m][n], 0, 0, 0); __builtin_amdgcn_s_setprio(0); } while (0)
; #define PG8_WAIT_V(n) asm volatile("s_waitcnt vmcnt(" #n ")" ::: "memory")
; #define PG8_WAIT_L(n) asm volatile("s_waitcnt lgkmcnt(" #n ")" ::: "memory")
; #define PG8_BAR __builtin_amdgcn_s_barrier()
; #define PG8_SCHED __builtin_amdgcn_sched_barrier(0)
;     ...
;             PG8_WAIT_V(8); PG8_WAIT_L(0); PG8_BAR; PG8_MMA(0, 0, At, B0); PG8_MMA(0, 1, At, B1); PG8_BAR; PG8_SCHED;
;             PG8_LDA(At, 0, 1); PG8_STAGE(PG8_SB(0, 0), b2, voffB); PG8_STAGE(PG8_SB(0, 1), b2 + hstepB, voffB); PG8_STAGE(PG8_SA(0, 0), a2, voffA);
;             PG8_WAIT_V(8); PG8_WAIT_L(0); PG8_BAR; PG8_MMA(1, 0, At, B0); PG8_MMA(1, 1, At, B1); PG8_BAR; PG8_SCHED;
;             PG8_LDB(B0, 1, 0); PG8_LDB(B1, 1, 1); PG8_SCHED; PG8_LDA(At, 1, 0); PG8_STAGE(PG8_SA(0, 1), a2 + hstep, voffA);
;             PG8_WAIT_V(8); PG8_WAIT_L(0); PG8_BAR; PG8_MMA(0, 0, At, B0); PG8_MMA(0, 1, At, B1); PG8_BAR; PG8_SCHED;
;             PG8_LDA(At, 1, 1); PG8_STAGE(PG8_SB(1, 0), b3, voffB); PG8_STAGE(PG8_SB(1, 1), b3 + hstepB, voffB); PG8_STAGE(PG8_SA(1, 0), a3, voffA);
	s_setprio 1
	s_waitcnt lgkmcnt(0)
	v_mfma_f32_16x16x32_bf16 v[62:65], v[146:149], v[178:181], 0
	v_mfma_f32_16x16x32_bf16 v[58:61], v[154:157], v[178:181], 0
	v_mfma_f32_16x16x32_bf16 v[50:53], v[146:149], v[186:189], 0
	v_mfma_f32_16x16x32_bf16 v[42:45], v[154:157], v[186:189], 0
	v_mfma_f32_16x16x32_bf16 v[34:37], v[146:149], v[194:197], 0
	v_mfma_f32_16x16x32_bf16 v[26:29], v[154:157], v[194:197], 0
	v_mfma_f32_16x16x32_bf16 v[18:21], v[146:149], v[202:205], 0
	v_mfma_f32_16x16x32_bf16 v[10:13], v[154:157], v[202:205], 0
	v_mfma_f32_16x16x32_bf16 v[62:65], v[150:153], v[182:185], v[62:65]
	v_mfma_f32_16x16x32_bf16 v[58:61], v[158:161], v[182:185], v[58:61]
	v_mfma_f32_16x16x32_bf16 v[50:53], v[150:153], v[190:193], v[50:53]
	v_mfma_f32_16x16x32_bf16 v[42:45], v[158:161], v[190:193], v[42:45]
	v_mfma_f32_16x16x32_bf16 v[34:37], v[150:153], v[198:201], v[34:37]
	v_mfma_f32_16x16x32_bf16 v[26:29], v[158:161], v[198:201], v[26:29]
	v_mfma_f32_16x16x32_bf16 v[18:21], v[150:153], v[206:209], v[18:21]
	v_mfma_f32_16x16x32_bf16 v[10:13], v[158:161], v[206:209], v[10:13]
	s_setprio 0
	s_setprio 1
	v_mfma_f32_16x16x32_bf16 v[54:57], v[162:165], v[178:181], 0
	v_mfma_f32_16x16x32_bf16 v[46:49], v[170:173], v[178:181], 0
	v_mfma_f32_16x16x32_bf16 v[38:41], v[162:165], v[186:189], 0
	v_mfma_f32_16x16x32_bf16 v[30:33], v[170:173], v[186:189], 0
	v_mfma_f32_16x16x32_bf16 v[22:25], v[162:165], v[194:197], 0
	v_mfma_f32_16x16x32_bf16 v[14:17], v[170:173], v[194:197], 0
	v_mfma_f32_16x16x32_bf16 v[6:9], v[162:165], v[202:205], 0
	v_mfma_f32_16x16x32_bf16 v[2:5], v[170:173], v[202:205], 0
	v_mfma_f32_16x16x32_bf16 v[54:57], v[166:169], v[182:185], v[54:57]
	v_mfma_f32_16x16x32_bf16 v[46:49], v[174:177], v[182:185], v[46:49]
	v_mfma_f32_16x16x32_bf16 v[38:41], v[166:169], v[190:193], v[38:41]
	v_mfma_f32_16x16x32_bf16 v[30:33], v[174:177], v[190:193], v[30:33]
	v_mfma_f32_16x16x32_bf16 v[22:25], v[166:169], v[198:201], v[22:25]
	v_mfma_f32_16x16x32_bf16 v[14:17], v[174:177], v[198:201], v[14:17]
	v_mfma_f32_16x16x32_bf16 v[6:9], v[166:169], v[206:209], v[6:9]
	v_mfma_f32_16x16x32_bf16 v[2:5], v[174:177], v[206:209], v[2:5]
	s_setprio 0
	s_barrier
	s_add_i32 s55, 0, 0x18000
	v_add_u32_e32 v136, s55, v141
	s_add_i32 s56, 0, 0x1c000
	ds_read_b128 v[146:149], v136
	ds_read_b128 v[150:153], v136 offset:1024
	ds_read_b128 v[154:157], v136 offset:2048
	ds_read_b128 v[158:161], v136 offset:3072
	v_add_u32_e32 v136, s56, v141
	ds_read_b128 v[162:165], v136
	ds_read_b128 v[166:169], v136 offset:1024
	ds_read_b128 v[170:173], v136 offset:2048
	ds_read_b128 v[174:177], v136 offset:3072
	s_add_u32 s18, s26, 0x40000
	s_addc_u32 s19, s27, 0
	v_mov_b32_e32 v136, v1
	s_mov_b32 m0, s31
	ds_read_b128 v[178:181], v144 offset:32768
	ds_read_b128 v[182:185], v144 offset:33792
	ds_read_b128 v[186:189], v144 offset:34816
	ds_read_b128 v[190:193], v144 offset:35840
	ds_read_b128 v[194:197], v144 offset:36864
	ds_read_b128 v[198:201], v144 offset:37888
	ds_read_b128 v[202:205], v144 offset:38912
	ds_read_b128 v[206:209], v144 offset:39936
	s_nop 0
	global_load_lds_dwordx4 v136, s[18:19]
	v_mov_b32_e32 v136, v139
	s_mov_b32 m0, s33
	s_nop 0
	global_load_lds_dwordx4 v136, s[18:19]
	s_waitcnt vmcnt(8)
	s_waitcnt lgkmcnt(0)
	s_barrier
	s_setprio 1
	s_waitcnt lgkmcnt(0)
	v_mfma_f32_16x16x32_bf16 v[126:129], v[146:149], v[178:181], v[126:129]
	v_mfma_f32_16x16x32_bf16 v[122:125], v[154:157], v[178:181], v[122:125]
	v_mfma_f32_16x16x32_bf16 v[114:117], v[146:149], v[186:189], v[114:117]
	v_mfma_f32_16x16x32_bf16 v[106:109], v[154:157], v[186:189], v[106:109]
	v_mfma_f32_16x16x32_bf16 v[98:101], v[146:149], v[194:197], v[98:101]
	v_mfma_f32_16x16x32_bf16 v[90:93], v[154:157], v[194:197], v[90:93]
	v_mfma_f32_16x16x32_bf16 v[82:85], v[146:149], v[202:205], v[82:85]
	v_mfma_f32_16x16x32_bf16 v[74:77], v[154:157], v[202:205], v[74:77]
	v_mfma_f32_16x16x32_bf16 v[126:129], v[150:153], v[182:185], v[126:129]
	v_mfma_f32_16x16x32_bf16 v[122:125], v[158:161], v[182:185], v[122:125]
	v_mfma_f32_16x16x32_bf16 v[114:117], v[150:153], v[190:193], v[114:117]
	v_mfma_f32_16x16x32_bf16 v[106:109], v[158:161], v[190:193], v[106:109]
	v_mfma_f32_16x16x32_bf16 v[98:101], v[150:153], v[198:201], v[98:101]
	v_mfma_f32_16x16x32_bf16 v[90:93], v[158:161], v[198:201], v[90:93]
	v_mfma_f32_16x16x32_bf16 v[82:85], v[150:153], v[206:209], v[82:85]
	v_mfma_f32_16x16x32_bf16 v[74:77], v[158:161], v[206:209], v[74:77]
	s_setprio 0
	s_setprio 1
	v_mfma_f32_16x16x32_bf16 v[118:121], v[162:165], v[178:181], v[118:121]
	v_mfma_f32_16x16x32_bf16 v[110:113], v[170:173], v[178:181], v[110:113]
	v_mfma_f32_16x16x32_bf16 v[102:105], v[162:165], v[186:189], v[102:105]
	v_mfma_f32_16x16x32_bf16 v[94:97], v[170:173], v[186:189], v[94:97]
	v_mfma_f32_16x16x32_bf16 v[86:89], v[162:165], v[194:197], v[86:89]
	v_mfma_f32_16x16x32_bf16 v[78:81], v[170:173], v[194:197], v[78:81]
	v_mfma_f32_16x16x32_bf16 v[70:73], v[162:165], v[202:205], v[70:73]
	v_mfma_f32_16x16x32_bf16 v[66:69], v[170:173], v[202:205], v[66:69]
	v_mfma_f32_16x16x32_bf16 v[118:121], v[166:169], v[182:185], v[118:121]
	v_mfma_f32_16x16x32_bf16 v[110:113], v[174:177], v[182:185], v[110:113]
	v_mfma_f32_16x16x32_bf16 v[102:105], v[166:169], v[190:193], v[102:105]
	v_mfma_f32_16x16x32_bf16 v[94:97], v[174:177], v[190:193], v[94:97]
	v_mfma_f32_16x16x32_bf16 v[86:89], v[166:169], v[198:201], v[86:89]
	v_mfma_f32_16x16x32_bf16 v[78:81], v[174:177], v[198:201], v[78:81]
	v_mfma_f32_16x16x32_bf16 v[70:73], v[166:169], v[206:209], v[70:73]
	v_mfma_f32_16x16x32_bf16 v[66:69], v[174:177], v[206:209], v[66:69]
	s_setprio 0
	s_barrier
; #define PG8_STAGE(bufoff, gbase, voff) do { const char* gb_ = (const char*)(gbase); asm volatile("" : "+s"(gb_)); _Pragma("unroll") for (int _i = 0; _i < 2; ++_i) { unsigned vo_ = (voff)[_i]; asm volatile("" : "+v"(vo_)); \
;         __builtin_amdgcn_global_load_lds((const unsigned*)(gb_ + vo_), (PG8_LAS unsigned*)(lds + (bufoff) + ldsw + _i * 8192), 16, 0, 0); } } while (0)
; #define PG8_LDA(dst, b, h) do { _Pragma("unroll") for (int m = 0; m < 4; ++m) _Pragma("unroll") for (int k = 0; k < 2; ++k) dst[m][k] = *(const PG8_LAS bf16x8*)(lds + PG8_SA(b, h) + aoff + m * 2048 + k * 1024); } while (0)
; #define PG8_LDB(dst, b, h) do { _Pragma("unroll") for (int n = 0; n < 2; ++n) _Pragma("unroll") for (int k = 0; k < 2; ++k) dst[n][k] = *(const PG8_LAS bf16x8*)(lds + PG8_SB(b, h) + boff + n * 2048 + k * 1024); } while (0)
; #define PG8_MMA(ai, bj, At, Bt) do { __builtin_amdgcn_s_setprio(1); _Pragma("unroll") for (int m = 0; m < 4; ++m) _Pragma("unroll") for (int n = 0; n < 2; ++n) _Pragma("unroll") for (int k = 0; k < 2; ++k) \
;         acc[ai][bj][m][n] = __builtin_amdgcn_mfma_f32_16x16x32_bf16(Bt[n][k], At[m][k], acc[ai][bj][m][n], 0, 0, 0); __builtin_amdgcn_s_setprio(0); } while (0)
; #define PG8_WAIT_V(n) asm volatile("s_waitcnt vmcnt(" #n ")" ::: "memory")
; #define PG8_WAIT_L(n) asm volatile("s_waitcnt lgkmcnt(" #n ")" ::: "memory")
; #define PG8_BAR __builtin_amdgcn_s_barrier()
; #define PG8_SCHED __builtin_amdgcn_sched_barrier(0)
;     ...
;             PG8_LDB(B0, 1, 0); PG8_LDB(B1, 1, 1); PG8_SCHED; PG8_LDA(At, 1, 0); PG8_STAGE(PG8_SA(0, 1), a2 + hstep, voffA);
;             PG8_WAIT_V(8); PG8_WAIT_L(0); PG8_BAR; PG8_MMA(0, 0, At, B0); PG8_MMA(0, 1, At, B1); PG8_BAR; PG8_SCHED;
;             PG8_LDA(At, 1, 1); PG8_STAGE(PG8_SB(1, 0), b3, voffB); PG8_STAGE(PG8_SB(1, 1), b3 + hstepB, voffB); PG8_STAGE(PG8_SA(1, 0), a3, voffA);
;             PG8_WAIT_V(8); PG8_WAIT_L(0); PG8_BAR; PG8_MMA(1, 0, At, B0); PG8_MMA(1, 1, At, B1); PG8_BAR; PG8_SCHED;
	s_add_u32 s18, s24, 0x80
	s_addc_u32 s19, s25, 0
	v_mov_b32_e32 v136, v138
	s_add_i32 s26, s55, s29
	ds_read_b128 v[178:181], v144 offset:49152
	ds_read_b128 v[182:185], v144 offset:50176
	ds_read_b128 v[186:189], v144 offset:51200
	ds_read_b128 v[190:193], v144 offset:52224
	ds_read_b128 v[194:197], v144 offset:53248
	ds_read_b128 v[198:201], v144 offset:54272
	ds_read_b128 v[202:205], v144 offset:55296
	ds_read_b128 v[206:209], v144 offset:56320
	s_mov_b32 m0, s26
	s_nop 0
	global_load_lds_dwordx4 v136, s[18:19]
	v_mov_b32_e32 v136, v140
	s_add_i32 m0, s26, 0x2000
	s_nop 0
	global_load_lds_dwordx4 v136, s[18:19]
	s_add_u32 s18, s24, 0x10080
	s_addc_u32 s19, s25, 0
	v_mov_b32_e32 v136, v138
	s_add_i32 s24, s56, s29
	s_mov_b32 m0, s24
	s_nop 0
	global_load_lds_dwordx4 v136, s[18:19]
	v_mov_b32_e32 v136, v140
	s_add_i32 m0, s24, 0x2000
	s_nop 0
	global_load_lds_dwordx4 v136, s[18:19]
	v_mov_b32_e32 v136, v1
	s_mov_b32 m0, s36
	s_nop 0
	global_load_lds_dwordx4 v136, s[22:23]
	v_mov_b32_e32 v136, v139
	s_mov_b32 m0, s37
	s_nop 0
	global_load_lds_dwordx4 v136, s[22:23]
	s_waitcnt vmcnt(8)
	s_waitcnt lgkmcnt(0)
	s_barrier
	s_setprio 1
	s_waitcnt lgkmcnt(0)
	v_mfma_f32_16x16x32_bf16 v[62:65], v[146:149], v[178:181], v[62:65]
	v_mfma_f32_16x16x32_bf16 v[58:61], v[154:157], v[178:181], v[58:61]
	v_mfma_f32_16x16x32_bf16 v[50:53], v[146:149], v[186:189], v[50:53]
	v_mfma_f32_16x16x32_bf16 v[42:45], v[154:157], v[186:189], v[42:45]
	v_mfma_f32_16x16x32_bf16 v[34:37], v[146:149], v[194:197], v[34:37]
	v_mfma_f32_16x16x32_bf16 v[26:29], v[154:157], v[194:197], v[26:29]
	v_mfma_f32_16x16x32_bf16 v[18:21], v[146:149], v[202:205], v[18:21]
	v_mfma_f32_16x16x32_bf16 v[10:13], v[154:157], v[202:205], v[10:13]
	v_mfma_f32_16x16x32_bf16 v[62:65], v[150:153], v[182:185], v[62:65]
	v_mfma_f32_16x16x32_bf16 v[58:61], v[158:161], v[182:185], v[58:61]
	v_mfma_f32_16x16x32_bf16 v[50:53], v[150:153], v[190:193], v[50:53]
	v_mfma_f32_16x16x32_bf16 v[42:45], v[158:161], v[190:193], v[42:45]
	v_mfma_f32_16x16x32_bf16 v[34:37], v[150:153], v[198:201], v[34:37]
	v_mfma_f32_16x16x32_bf16 v[26:29], v[158:161], v[198:201], v[26:29]
	v_mfma_f32_16x16x32_bf16 v[18:21], v[150:153], v[206:209], v[18:21]
	v_mfma_f32_16x16x32_bf16 v[10:13], v[158:161], v[206:209], v[10:13]
	s_setprio 0
	s_setprio 1
	v_mfma_f32_16x16x32_bf16 v[54:57], v[162:165], v[178:181], v[54:57]
	v_mfma_f32_16x16x32_bf16 v[46:49], v[170:173], v[178:181], v[46:49]
	v_mfma_f32_16x16x32_bf16 v[38:41], v[162:165], v[186:189], v[38:41]
	v_mfma_f32_16x16x32_bf16 v[30:33], v[170:173], v[186:189], v[30:33]
	v_mfma_f32_16x16x32_bf16 v[22:25], v[162:165], v[194:197], v[22:25]
	v_mfma_f32_16x16x32_bf16 v[14:17], v[170:173], v[194:197], v[14:17]
	v_mfma_f32_16x16x32_bf16 v[6:9], v[162:165], v[202:205], v[6:9]
	v_mfma_f32_16x16x32_bf16 v[2:5], v[170:173], v[202:205], v[2:5]
	v_mfma_f32_16x16x32_bf16 v[54:57], v[166:169], v[182:185], v[54:57]
	v_mfma_f32_16x16x32_bf16 v[46:49], v[174:177], v[182:185], v[46:49]
	v_mfma_f32_16x16x32_bf16 v[38:41], v[166:169], v[190:193], v[38:41]
	v_mfma_f32_16x16x32_bf16 v[30:33], v[174:177], v[190:193], v[30:33]
	v_mfma_f32_16x16x32_bf16 v[22:25], v[166:169], v[198:201], v[22:25]
	v_mfma_f32_16x16x32_bf16 v[14:17], v[174:177], v[198:201], v[14:17]
	v_mfma_f32_16x16x32_bf16 v[6:9], v[166:169], v[206:209], v[6:9]
	v_mfma_f32_16x16x32_bf16 v[2:5], v[174:177], v[206:209], v[2:5]
	s_setprio 0
	s_barrier
	s_add_i32 s54, s54, 2
	s_add_u32 s52, s52, 0x100
	s_addc_u32 s53, s53, 0
	s_cmp_gt_u32 s54, 13
	s_mov_b64 s[18:19], s[20:21]

; #define PG8_WAIT_V(n) asm volatile("s_waitcnt vmcnt(" #n ")" ::: "memory")
; #define PG8_BAR __builtin_amdgcn_s_barrier()
;     const int tid = threadIdx.x, wid = __builtin_amdgcn_readfirstlane(tid >> 6), lane = tid & 63, wr = wid >> 2, wc = wid & 3, fr = lane & 15, fq = lane >> 4;
;     const int nt = K / BK;
;     unsigned voffA[2], voffB[2];
; #pragma unroll
;     for (int i = 0; i < 2; ++i) { int R, C; stage_rc(tid * 16 + i * 8192, R, C); const int Rb = Epi::PERM64 ? (64 * (R >> 5) + perm32(R & 31)) : Epi::PERM ? ((R & ~31) + perm32(R & 31)) : R;
;         voffA[i] = (unsigned)(R * K + C) * 2u; voffB[i] = (unsigned)(Rb * K + C) * 2u; }
;     const size_t kstep = (size_t)(BK * 2);
;     const size_t hstep = (size_t)HALF * K * 2;
;     const size_t hstepB = Epi::PERM64 ? (size_t)32 * K * 2 : hstep;
;     const unsigned ldsw = (unsigned)wid * 1024u;
;     const int aoff = lds_byte(wr * 64 + fr, fq * 8), boff = lds_byte(wc * 32 + fr, fq * 8);
;     ...
;     Unit cur, nxt; int ui = 0;
;     if (!S.next(0, cur)) return;
;     f32x4 acc[2][2][4][2];
;     if constexpr (!DE) {
; #pragma unroll
;     for (int a = 0; a < 2; ++a)
; #pragma unroll
;         for (int b = 0; b < 2; ++b)
; #pragma unroll
;             for (int m = 0; m < 4; ++m)
; #pragma unroll
;                 for (int n = 0; n < 2; ++n) acc[a][b][m][n] = (f32x4){0.f, 0.f, 0.f, 0.f};
;     }
;     bf16x8 At[4][2], B0[2][2], B1[2][2];
;     const char* cA = S.a_ptr(cur); const char* cB = S.b_ptr(cur);
;     S.a_ready(cur);
;     if constexpr (SP2) {
;         PG8_STAGE(PG8_SB(0, 0), cB, voffB); PG8_STAGE(PG8_SB(0, 1), cB + hstepB, voffB); PG8_STAGE(PG8_SA(0, 0), cA, voffA); PG8_STAGE(PG8_SA(0, 1), cA + hstep, voffA);
;         if (wr == 1) PG8_BAR;
;         PG8_WAIT_V(2); PG8_BAR;
;         PG8_STAGE(PG8_SB(1, 0), cB + kstep, voffB); PG8_STAGE(PG8_SA(1, 0), cA + kstep, voffA); PG8_STAGE(PG8_SB(1, 1), cB + hstepB + kstep, voffB);
;         PG8_WAIT_V(6); PG8_BAR;
;     } else {
;         PG8_STAGE(PG8_SB(0, 0), cB, voffB); PG8_STAGE(PG8_SA(0, 0), cA, voffA); PG8_STAGE(PG8_SB(0, 1), cB + hstepB, voffB); PG8_STAGE(PG8_SA(0, 1), cA + hstep, voffA);
;         if (wr == 1) PG8_BAR;
;         PG8_WAIT_V(4); PG8_BAR;
;         PG8_STAGE(PG8_SB(1, 0), cB + kstep, voffB); PG8_STAGE(PG8_SA(1, 0), cA + kstep, voffA); PG8_STAGE(PG8_SB(1, 1), cB + hstepB + kstep, voffB);
;         PG8_WAIT_V(6); PG8_BAR;
.LBB0_965:
	v_and_b32_e32 v137, 15, v0
	v_lshlrev_b32_e32 v1, 1, v132
	v_lshlrev_b32_e32 v3, 2, v0
	s_sext_i32_i8 s34, s0
	v_lshl_or_b32 v2, v137, 6, v1
	s_lshl_b32 s0, s1, 13
	v_and_b32_e32 v3, 32, v3
	v_bitop3_b32 v2, v2, s0, v3 bitop3:0xde
	s_lshl_b32 s0, s2, 5
	s_and_b32 s37, s0, 0x60
	v_lshlrev_b32_e32 v0, 6, v0
	s_movk_i32 s0, 0x3c0
	s_lshl_b32 s36, s1, 6
	v_and_or_b32 v0, v0, s0, v1
	s_lshl_b32 s0, s37, 7
	v_bitop3_b32 v138, s0, v0, v3 bitop3:0xf6
	s_add_u32 s0, s10, 0x80
	s_addc_u32 s1, s11, 0
	v_mov_b32_e32 v0, v134
	s_waitcnt vmcnt(2)
	s_barrier
	s_add_i32 m0, s7, 0x18000
	v_mov_b64_e32 v[128:129], 0x100
	global_load_lds_dwordx4 v0, s[0:1]
	v_mov_b32_e32 v0, v136
	s_add_i32 m0, s7, 0x1a000
	v_mov_b64_e32 v[130:131], 0xff
	global_load_lds_dwordx4 v0, s[0:1]
	s_add_u32 s0, s12, 0x80
	s_addc_u32 s1, s13, 0
	v_mov_b32_e32 v0, v133
	s_add_i32 s39, s7, 0x8000
	s_mov_b32 m0, s39
	s_add_i32 s40, s7, 0xa000
	global_load_lds_dwordx4 v0, s[0:1]
	v_mov_b32_e32 v0, v135
	s_mov_b32 m0, s40
	v_add_u32_e32 v139, 0, v2
	global_load_lds_dwordx4 v0, s[0:1]
	s_add_u32 s0, s10, 0x100080
	s_addc_u32 s1, s11, 0
	v_mov_b32_e32 v0, v134
	s_add_i32 m0, s7, 0x1c000
	s_add_i32 s41, 0, 0x10000
	global_load_lds_dwordx4 v0, s[0:1]
	v_mov_b32_e32 v0, v136
	s_add_i32 m0, s7, 0x1e000
	s_add_i32 s42, 0, 0x14000
	global_load_lds_dwordx4 v0, s[0:1]
	s_waitcnt vmcnt(6)
	s_barrier
	s_branch .LBB0_967

;     __device__ __forceinline__ bool next(int i, Unit& u) const { const long L = (long)i * G + c; if (L >= (long)nM * nN) return false; static_tile((int)L, nM, nN, u.pm, u.pn); u.br = 0; return true; }
;     __device__ __forceinline__ bool next(int i, Unit& u) const { if (i >= 1 || c >= 256) return false; static_tile(c, 64, 4, u.pm, u.pn); u.br = br; return true; }
;     __device__ __forceinline__ bool next(int i, Unit& u) const { if (i >= 3 || c >= 256) return false; static_tile(c, 64, 4, u.pm, u.pn); u.br = i; return true; }
; #define PG8_STAGE(bufoff, gbase, voff) do { const char* gb_ = (const char*)(gbase); asm volatile("" : "+s"(gb_)); _Pragma("unroll") for (int _i = 0; _i < 2; ++_i) { unsigned vo_ = (voff)[_i]; asm volatile("" : "+v"(vo_)); \
;         __builtin_amdgcn_global_load_lds((const unsigned*)(gb_ + vo_), (PG8_LAS unsigned*)(lds + (bufoff) + ldsw + _i * 8192), 16, 0, 0); } } while (0)
; #define PG8_LDA(dst, b, h) do { _Pragma("unroll") for (int m = 0; m < 4; ++m) _Pragma("unroll") for (int k = 0; k < 2; ++k) dst[m][k] = *(const PG8_LAS bf16x8*)(lds + PG8_SA(b, h) + aoff + m * 2048 + k * 1024); } while (0)
;     ...
;         const bool has_next = S.next(ui + 1, nxt);
;         if (GP) gpU = __builtin_amdgcn_s_memrealtime();
;         const char* nA = has_next ? S.a_ptr(nxt) : cA; const char* nB = has_next ? S.b_ptr(nxt) : cB;
;         for (int t = 0; t < nt; t += 2) {
;             const bool last = (t == nt - 2);
;             if (GP && t == 2) gp1 = __builtin_amdgcn_s_memrealtime();
;             const char* a1 = cA + (size_t)(t + 1) * kstep;
;             const char* a2 = last ? nA : cA + (size_t)(t + 2) * kstep; const char* b2 = last ? nB : cB + (size_t)(t + 2) * kstep;
;             const char* a3 = a2 + kstep; const char* b3 = b2 + kstep;
;             if (last && has_next) S.a_ready(nxt);
;             if constexpr (SP2) {
;             PG8_LDB(B0, 0, 0); PG8_LDB(B1, 0, 1); PG8_SCHED; PG8_LDA(At, 0, 0); PG8_STAGE(PG8_SA(1, 1), a1 + hstep, voffA);
;             PG8_WAIT_V(8); PG8_WAIT_L(0); PG8_BAR; PG8_MMA(0, 0, At, B0); PG8_MMA(0, 1, At, B1); PG8_BAR; PG8_SCHED;
;             PG8_LDA(At, 0, 1); PG8_STAGE(PG8_SB(0, 0), b2, voffB); PG8_STAGE(PG8_SB(0, 1), b2 + hstepB, voffB); PG8_STAGE(PG8_SA(0, 0), a2, voffA);
;             PG8_WAIT_V(8); PG8_WAIT_L(0); PG8_BAR; PG8_MMA(1, 0, At, B0); PG8_MMA(1, 1, At, B1); PG8_BAR; PG8_SCHED;
.LBB0_973:
	s_ashr_i32 s17, s16, 31
	s_lshl_b64 s[2:3], s[16:17], 21
	s_add_u32 s2, s82, s2
	s_addc_u32 s3, s83, s3
	s_and_b64 s[18:19], s[4:5], exec
	s_cselect_b32 s17, s3, s13
	s_cselect_b32 s44, s2, s12
	s_ashr_i32 s15, s14, 31
	s_lshl_b64 s[18:19], s[14:15], 21
	s_add_u32 s18, s50, s18
	s_addc_u32 s19, s51, s19
	s_and_b64 s[20:21], s[4:5], exec
	s_cselect_b32 s15, s19, s11
	s_cselect_b32 s45, s18, s10
	s_mov_b32 s46, -2
	s_mov_b64 s[20:21], 0
	s_add_u32 s47, s12, s20
	s_addc_u32 s49, s13, s21
	s_add_u32 s22, s47, 0x100
	s_addc_u32 s23, s49, 0
	v_add_u32_e32 v152, s41, v138
	v_add_u32_e32 v168, s42, v138
	s_add_u32 s24, s10, s20
	ds_read_b128 v[140:143], v152
	ds_read_b128 v[144:147], v152 offset:1024
	ds_read_b128 v[148:151], v152 offset:2048
	ds_read_b128 v[152:155], v152 offset:3072
	ds_read_b128 v[156:159], v168
	ds_read_b128 v[160:163], v168 offset:1024
	ds_read_b128 v[164:167], v168 offset:2048
	ds_read_b128 v[168:171], v168 offset:3072
	s_addc_u32 s25, s11, s21
	s_add_u32 s24, s24, 0x100
	s_addc_u32 s25, s25, 0
	s_cmp_eq_u32 s46, 60
	s_cselect_b32 s26, s44, s22
	s_cselect_b32 s27, s17, s23
	s_cselect_b32 s24, s45, s24
	s_cselect_b32 s25, s15, s25
	s_add_u32 s22, s26, 0x80
	s_addc_u32 s23, s27, 0
	s_add_u32 s48, s47, 0x100080
	s_addc_u32 s49, s49, 0
	v_mov_b32_e32 v204, v133
	s_waitcnt lgkmcnt(7)
	ds_read_b128 v[172:175], v139
	ds_read_b128 v[176:179], v139 offset:1024
	ds_read_b128 v[180:183], v139 offset:2048
	ds_read_b128 v[184:187], v139 offset:3072
	ds_read_b128 v[188:191], v139 offset:4096
	ds_read_b128 v[192:195], v139 offset:5120
	ds_read_b128 v[196:199], v139 offset:6144
	ds_read_b128 v[200:203], v139 offset:7168
	s_add_i32 m0, s7, 0xc000
	s_nop 0
	global_load_lds_dwordx4 v204, s[48:49]
	v_mov_b32_e32 v204, v135
	s_add_i32 m0, s7, 0xe000
	s_nop 0
	global_load_lds_dwordx4 v204, s[48:49]
	s_waitcnt vmcnt(8)
	s_waitcnt lgkmcnt(0)
	s_barrier
	s_setprio 1
	s_waitcnt lgkmcnt(0)
	v_mfma_f32_16x16x32_bf16 v[124:127], v[140:143], v[172:175], 0
	v_mfma_f32_16x16x32_bf16 v[120:123], v[148:151], v[172:175], 0
	v_mfma_f32_16x16x32_bf16 v[108:111], v[140:143], v[180:183], 0
	v_mfma_f32_16x16x32_bf16 v[104:107], v[148:151], v[180:183], 0
	v_mfma_f32_16x16x32_bf16 v[92:95], v[140:143], v[188:191], 0
	v_mfma_f32_16x16x32_bf16 v[88:91], v[148:151], v[188:191], 0
	v_mfma_f32_16x16x32_bf16 v[76:79], v[140:143], v[196:199], 0
	v_mfma_f32_16x16x32_bf16 v[72:75], v[148:151], v[196:199], 0
	v_mfma_f32_16x16x32_bf16 v[124:127], v[144:147], v[176:179], v[124:127]
	v_mfma_f32_16x16x32_bf16 v[120:123], v[152:155], v[176:179], v[120:123]
	v_mfma_f32_16x16x32_bf16 v[108:111], v[144:147], v[184:187], v[108:111]
	v_mfma_f32_16x16x32_bf16 v[104:107], v[152:155], v[184:187], v[104:107]
	v_mfma_f32_16x16x32_bf16 v[92:95], v[144:147], v[192:195], v[92:95]
	v_mfma_f32_16x16x32_bf16 v[88:91], v[152:155], v[192:195], v[88:91]
	v_mfma_f32_16x16x32_bf16 v[76:79], v[144:147], v[200:203], v[76:79]
	v_mfma_f32_16x16x32_bf16 v[72:75], v[152:155], v[200:203], v[72:75]
	s_setprio 0
	s_setprio 1
	v_mfma_f32_16x16x32_bf16 v[116:119], v[156:159], v[172:175], 0
	v_mfma_f32_16x16x32_bf16 v[112:115], v[164:167], v[172:175], 0
	v_mfma_f32_16x16x32_bf16 v[100:103], v[156:159], v[180:183], 0
	v_mfma_f32_16x16x32_bf16 v[96:99], v[164:167], v[180:183], 0
	v_mfma_f32_16x16x32_bf16 v[84:87], v[156:159], v[188:191], 0
	v_mfma_f32_16x16x32_bf16 v[80:83], v[164:167], v[188:191], 0
	v_mfma_f32_16x16x32_bf16 v[68:71], v[156:159], v[196:199], 0
	v_mfma_f32_16x16x32_bf16 v[64:67], v[164:167], v[196:199], 0
	v_mfma_f32_16x16x32_bf16 v[116:119], v[160:163], v[176:179], v[116:119]
	v_mfma_f32_16x16x32_bf16 v[112:115], v[168:171], v[176:179], v[112:115]
	v_mfma_f32_16x16x32_bf16 v[100:103], v[160:163], v[184:187], v[100:103]
	v_mfma_f32_16x16x32_bf16 v[96:99], v[168:171], v[184:187], v[96:99]
	v_mfma_f32_16x16x32_bf16 v[84:87], v[160:163], v[192:195], v[84:87]
	v_mfma_f32_16x16x32_bf16 v[80:83], v[168:171], v[192:195], v[80:83]
	v_mfma_f32_16x16x32_bf16 v[68:71], v[160:163], v[200:203], v[68:71]
	v_mfma_f32_16x16x32_bf16 v[64:67], v[168:171], v[200:203], v[64:67]
	s_setprio 0
	s_barrier
	s_mov_b64 s[48:49], s[24:25]
	v_mov_b32_e32 v204, v134
	s_add_i32 s47, s41, s30
	ds_read_b128 v[172:175], v139 offset:16384
	ds_read_b128 v[176:179], v139 offset:17408
	ds_read_b128 v[180:183], v139 offset:18432
	ds_read_b128 v[184:187], v139 offset:19456
	ds_read_b128 v[188:191], v139 offset:20480
	ds_read_b128 v[192:195], v139 offset:21504
	ds_read_b128 v[196:199], v139 offset:22528
	ds_read_b128 v[200:203], v139 offset:23552
	s_mov_b32 m0, s47
	s_nop 0
	global_load_lds_dwordx4 v204, s[48:49]
	v_mov_b32_e32 v204, v136
	s_add_i32 m0, s47, 0x2000
	s_nop 0
	global_load_lds_dwordx4 v204, s[48:49]
	s_add_u32 s48, s24, 0x100000
	s_addc_u32 s49, s25, 0
	v_mov_b32_e32 v204, v134
	s_add_i32 s47, s42, s30
	s_mov_b32 m0, s47
	s_nop 0
	global_load_lds_dwordx4 v204, s[48:49]
	v_mov_b32_e32 v204, v136
	s_add_i32 m0, s47, 0x2000
	s_nop 0
	global_load_lds_dwordx4 v204, s[48:49]
	s_mov_b64 s[48:49], s[26:27]
	v_mov_b32_e32 v204, v133
	s_mov_b32 m0, s7
	s_nop 0
	global_load_lds_dwordx4 v204, s[48:49]
	v_mov_b32_e32 v204, v135
	s_mov_b32 m0, s31
	s_nop 0
	global_load_lds_dwordx4 v204, s[48:49]
	s_waitcnt vmcnt(8)
	s_waitcnt lgkmcnt(0)
	s_barrier
; #define PG8_STAGE(bufoff, gbase, voff) do { const char* gb_ = (const char*)(gbase); asm volatile("" : "+s"(gb_)); _Pragma("unroll") for (int _i = 0; _i < 2; ++_i) { unsigned vo_ = (voff)[_i]; asm volatile("" : "+v"(vo_)); \
;         __builtin_amdgcn_global_load_lds((const unsigned*)(gb_ + vo_), (PG8_LAS unsigned*)(lds + (bufoff) + ldsw + _i * 8192), 16, 0, 0); } } while (0)
; #define PG8_LDA(dst, b, h) do { _Pragma("unroll") for (int m = 0; m < 4; ++m) _Pragma("unroll") for (int k = 0; k < 2; ++k) dst[m][k] = *(const PG8_LAS bf16x8*)(lds + PG8_SA(b, h) + aoff + m * 2048 + k * 1024); } while (0)
; #define PG8_LDB(dst, b, h) do { _Pragma("unroll") for (int n = 0; n < 2; ++n) _Pragma("unroll") for (int k = 0; k < 2; ++k) dst[n][k] = *(const PG8_LAS bf16x8*)(lds + PG8_SB(b, h) + boff + n * 2048 + k * 1024); } while (0)
; #define PG8_MMA(ai, bj, At, Bt) do { __builtin_amdgcn_s_setprio(1); _Pragma("unroll") for (int m = 0; m < 4; ++m) _Pragma("unroll") for (int n = 0; n < 2; ++n) _Pragma("unroll") for (int k = 0; k < 2; ++k) \
;         acc[ai][bj][m][n] = __builtin_amdgcn_mfma_f32_16x16x32_bf16(Bt[n][k], At[m][k], acc[ai][bj][m][n], 0, 0, 0); __builtin_amdgcn_s_setprio(0); } while (0)
; #define PG8_WAIT_V(n) asm volatile("s_waitcnt vmcnt(" #n ")" ::: "memory")
; #define PG8_WAIT_L(n) asm volatile("s_waitcnt lgkmcnt(" #n ")" ::: "memory")
; #define PG8_BAR __builtin_amdgcn_s_barrier()
; #define PG8_SCHED __builtin_amdgcn_sched_barrier(0)
;     ...
;             PG8_LDA(At, 0, 1); PG8_STAGE(PG8_SB(0, 0), b2, voffB); PG8_STAGE(PG8_SB(0, 1), b2 + hstepB, voffB); PG8_STAGE(PG8_SA(0, 0), a2, voffA);
;             PG8_WAIT_V(8); PG8_WAIT_L(0); PG8_BAR; PG8_MMA(1, 0, At, B0); PG8_MMA(1, 1, At, B1); PG8_BAR; PG8_SCHED;
;             PG8_LDB(B0, 1, 0); PG8_LDB(B1, 1, 1); PG8_SCHED; PG8_LDA(At, 1, 0); PG8_STAGE(PG8_SA(0, 1), a2 + hstep, voffA);
;             PG8_WAIT_V(8); PG8_WAIT_L(0); PG8_BAR; PG8_MMA(0, 0, At, B0); PG8_MMA(0, 1, At, B1); PG8_BAR; PG8_SCHED;
	s_setprio 1
	s_waitcnt lgkmcnt(0)
	v_mfma_f32_16x16x32_bf16 v[60:63], v[140:143], v[172:175], 0
	v_mfma_f32_16x16x32_bf16 v[56:59], v[148:151], v[172:175], 0
	v_mfma_f32_16x16x32_bf16 v[44:47], v[140:143], v[180:183], 0
	v_mfma_f32_16x16x32_bf16 v[40:43], v[148:151], v[180:183], 0
	v_mfma_f32_16x16x32_bf16 v[28:31], v[140:143], v[188:191], 0
	v_mfma_f32_16x16x32_bf16 v[24:27], v[148:151], v[188:191], 0
	v_mfma_f32_16x16x32_bf16 v[12:15], v[140:143], v[196:199], 0
	v_mfma_f32_16x16x32_bf16 v[8:11], v[148:151], v[196:199], 0
	v_mfma_f32_16x16x32_bf16 v[60:63], v[144:147], v[176:179], v[60:63]
	v_mfma_f32_16x16x32_bf16 v[56:59], v[152:155], v[176:179], v[56:59]
	v_mfma_f32_16x16x32_bf16 v[44:47], v[144:147], v[184:187], v[44:47]
	v_mfma_f32_16x16x32_bf16 v[40:43], v[152:155], v[184:187], v[40:43]
	v_mfma_f32_16x16x32_bf16 v[28:31], v[144:147], v[192:195], v[28:31]
	v_mfma_f32_16x16x32_bf16 v[24:27], v[152:155], v[192:195], v[24:27]
	v_mfma_f32_16x16x32_bf16 v[12:15], v[144:147], v[200:203], v[12:15]
	v_mfma_f32_16x16x32_bf16 v[8:11], v[152:155], v[200:203], v[8:11]
	s_setprio 0
	s_setprio 1
	v_mfma_f32_16x16x32_bf16 v[52:55], v[156:159], v[172:175], 0
	v_mfma_f32_16x16x32_bf16 v[48:51], v[164:167], v[172:175], 0
	v_mfma_f32_16x16x32_bf16 v[36:39], v[156:159], v[180:183], 0
	v_mfma_f32_16x16x32_bf16 v[32:35], v[164:167], v[180:183], 0
	v_mfma_f32_16x16x32_bf16 v[20:23], v[156:159], v[188:191], 0
	v_mfma_f32_16x16x32_bf16 v[16:19], v[164:167], v[188:191], 0
	v_mfma_f32_16x16x32_bf16 v[4:7], v[156:159], v[196:199], 0
	v_mfma_f32_16x16x32_bf16 v[0:3], v[164:167], v[196:199], 0
	v_mfma_f32_16x16x32_bf16 v[52:55], v[160:163], v[176:179], v[52:55]
	v_mfma_f32_16x16x32_bf16 v[48:51], v[168:171], v[176:179], v[48:51]
	v_mfma_f32_16x16x32_bf16 v[36:39], v[160:163], v[184:187], v[36:39]
	v_mfma_f32_16x16x32_bf16 v[32:35], v[168:171], v[184:187], v[32:35]
	v_mfma_f32_16x16x32_bf16 v[20:23], v[160:163], v[192:195], v[20:23]
	v_mfma_f32_16x16x32_bf16 v[16:19], v[168:171], v[192:195], v[16:19]
	v_mfma_f32_16x16x32_bf16 v[4:7], v[160:163], v[200:203], v[4:7]
	v_mfma_f32_16x16x32_bf16 v[0:3], v[168:171], v[200:203], v[0:3]
	s_setprio 0
	s_barrier
	s_add_i32 s47, 0, 0x18000
	s_add_i32 s48, 0, 0x1c000
	v_add_u32_e32 v152, s47, v138
	v_add_u32_e32 v168, s48, v138
	ds_read_b128 v[140:143], v152
	ds_read_b128 v[144:147], v152 offset:1024
	ds_read_b128 v[148:151], v152 offset:2048
	ds_read_b128 v[152:155], v152 offset:3072
	ds_read_b128 v[156:159], v168
	ds_read_b128 v[160:163], v168 offset:1024
	ds_read_b128 v[164:167], v168 offset:2048
	ds_read_b128 v[168:171], v168 offset:3072
	s_add_u32 s26, s26, 0x100000
	s_addc_u32 s27, s27, 0
	v_mov_b32_e32 v204, v133
	s_mov_b32 m0, s33
	ds_read_b128 v[172:175], v139 offset:32768
	ds_read_b128 v[176:179], v139 offset:33792
	ds_read_b128 v[180:183], v139 offset:34816
	ds_read_b128 v[184:187], v139 offset:35840
	ds_read_b128 v[188:191], v139 offset:36864
	ds_read_b128 v[192:195], v139 offset:37888
	ds_read_b128 v[196:199], v139 offset:38912
	ds_read_b128 v[200:203], v139 offset:39936
	s_nop 0
	global_load_lds_dwordx4 v204, s[26:27]
	v_mov_b32_e32 v204, v135
	s_mov_b32 m0, s35
	s_nop 0
	global_load_lds_dwordx4 v204, s[26:27]
	s_waitcnt vmcnt(8)
	s_waitcnt lgkmcnt(0)
	s_barrier
	s_setprio 1
	s_waitcnt lgkmcnt(0)
	v_mfma_f32_16x16x32_bf16 v[124:127], v[140:143], v[172:175], v[124:127]
	v_mfma_f32_16x16x32_bf16 v[120:123], v[148:151], v[172:175], v[120:123]
	v_mfma_f32_16x16x32_bf16 v[108:111], v[140:143], v[180:183], v[108:111]
	v_mfma_f32_16x16x32_bf16 v[104:107], v[148:151], v[180:183], v[104:107]
	v_mfma_f32_16x16x32_bf16 v[92:95], v[140:143], v[188:191], v[92:95]
	v_mfma_f32_16x16x32_bf16 v[88:91], v[148:151], v[188:191], v[88:91]
	v_mfma_f32_16x16x32_bf16 v[76:79], v[140:143], v[196:199], v[76:79]
	v_mfma_f32_16x16x32_bf16 v[72:75], v[148:151], v[196:199], v[72:75]
	v_mfma_f32_16x16x32_bf16 v[124:127], v[144:147], v[176:179], v[124:127]
	v_mfma_f32_16x16x32_bf16 v[120:123], v[152:155], v[176:179], v[120:123]
	v_mfma_f32_16x16x32_bf16 v[108:111], v[144:147], v[184:187], v[108:111]
	v_mfma_f32_16x16x32_bf16 v[104:107], v[152:155], v[184:187], v[104:107]
	v_mfma_f32_16x16x32_bf16 v[92:95], v[144:147], v[192:195], v[92:95]
	v_mfma_f32_16x16x32_bf16 v[88:91], v[152:155], v[192:195], v[88:91]
	v_mfma_f32_16x16x32_bf16 v[76:79], v[144:147], v[200:203], v[76:79]
	v_mfma_f32_16x16x32_bf16 v[72:75], v[152:155], v[200:203], v[72:75]
	s_setprio 0
	s_setprio 1
	v_mfma_f32_16x16x32_bf16 v[116:119], v[156:159], v[172:175], v[116:119]
	v_mfma_f32_16x16x32_bf16 v[112:115], v[164:167], v[172:175], v[112:115]
	v_mfma_f32_16x16x32_bf16 v[100:103], v[156:159], v[180:183], v[100:103]
	v_mfma_f32_16x16x32_bf16 v[96:99], v[164:167], v[180:183], v[96:99]
	v_mfma_f32_16x16x32_bf16 v[84:87], v[156:159], v[188:191], v[84:87]
	v_mfma_f32_16x16x32_bf16 v[80:83], v[164:167], v[188:191], v[80:83]
	v_mfma_f32_16x16x32_bf16 v[68:71], v[156:159], v[196:199], v[68:71]
	v_mfma_f32_16x16x32_bf16 v[64:67], v[164:167], v[196:199], v[64:67]
	v_mfma_f32_16x16x32_bf16 v[116:119], v[160:163], v[176:179], v[116:119]
	v_mfma_f32_16x16x32_bf16 v[112:115], v[168:171], v[176:179], v[112:115]
	v_mfma_f32_16x16x32_bf16 v[100:103], v[160:163], v[184:187], v[100:103]
	v_mfma_f32_16x16x32_bf16 v[96:99], v[168:171], v[184:187], v[96:99]
	v_mfma_f32_16x16x32_bf16 v[84:87], v[160:163], v[192:195], v[84:87]
	v_mfma_f32_16x16x32_bf16 v[80:83], v[168:171], v[192:195], v[80:83]
	v_mfma_f32_16x16x32_bf16 v[68:71], v[160:163], v[200:203], v[68:71]
	v_mfma_f32_16x16x32_bf16 v[64:67], v[168:171], v[200:203], v[64:67]
	s_setprio 0
	s_barrier
; #define PG8_STAGE(bufoff, gbase, voff) do { const char* gb_ = (const char*)(gbase); asm volatile("" : "+s"(gb_)); _Pragma("unroll") for (int _i = 0; _i < 2; ++_i) { unsigned vo_ = (voff)[_i]; asm volatile("" : "+v"(vo_)); \
;         __builtin_amdgcn_global_load_lds((const unsigned*)(gb_ + vo_), (PG8_LAS unsigned*)(lds + (bufoff) + ldsw + _i * 8192), 16, 0, 0); } } while (0)
; #define PG8_LDA(dst, b, h) do { _Pragma("unroll") for (int m = 0; m < 4; ++m) _Pragma("unroll") for (int k = 0; k < 2; ++k) dst[m][k] = *(const PG8_LAS bf16x8*)(lds + PG8_SA(b, h) + aoff + m * 2048 + k * 1024); } while (0)
; #define PG8_LDB(dst, b, h) do { _Pragma("unroll") for (int n = 0; n < 2; ++n) _Pragma("unroll") for (int k = 0; k < 2; ++k) dst[n][k] = *(const PG8_LAS bf16x8*)(lds + PG8_SB(b, h) + boff + n * 2048 + k * 1024); } while (0)
; #define PG8_MMA(ai, bj, At, Bt) do { __builtin_amdgcn_s_setprio(1); _Pragma("unroll") for (int m = 0; m < 4; ++m) _Pragma("unroll") for (int n = 0; n < 2; ++n) _Pragma("unroll") for (int k = 0; k < 2; ++k) \
;         acc[ai][bj][m][n] = __builtin_amdgcn_mfma_f32_16x16x32_bf16(Bt[n][k], At[m][k], acc[ai][bj][m][n], 0, 0, 0); __builtin_amdgcn_s_setprio(0); } while (0)
; #define PG8_WAIT_V(n) asm volatile("s_waitcnt vmcnt(" #n ")" ::: "memory")
; #define PG8_WAIT_L(n) asm volatile("s_waitcnt lgkmcnt(" #n ")" ::: "memory")
; #define PG8_BAR __builtin_amdgcn_s_barrier()
; #define PG8_SCHED __builtin_amdgcn_sched_barrier(0)
;     ...
;             PG8_LDB(B0, 0, 0); PG8_LDB(B1, 0, 1); PG8_SCHED; PG8_LDA(At, 0, 0); PG8_STAGE(PG8_SA(1, 1), a1 + hstep, voffA);
;             PG8_WAIT_V(8); PG8_WAIT_L(0); PG8_BAR; PG8_MMA(0, 0, At, B0); PG8_MMA(0, 1, At, B1); PG8_BAR; PG8_SCHED;
;     ...
;             PG8_WAIT_V(8); PG8_WAIT_L(0); PG8_BAR; PG8_MMA(0, 0, At, B0); PG8_MMA(0, 1, At, B1); PG8_BAR; PG8_SCHED;
;             PG8_LDA(At, 1, 1); PG8_STAGE(PG8_SB(1, 0), b3, voffB); PG8_STAGE(PG8_SB(1, 1), b3 + hstepB, voffB); PG8_STAGE(PG8_SA(1, 0), a3, voffA);
;             PG8_WAIT_V(8); PG8_WAIT_L(0); PG8_BAR; PG8_MMA(1, 0, At, B0); PG8_MMA(1, 1, At, B1); PG8_BAR; PG8_SCHED;
	s_add_u32 s26, s24, 0x80
	s_addc_u32 s27, s25, 0
	v_mov_b32_e32 v204, v134
	s_add_i32 s47, s47, s30
	ds_read_b128 v[172:175], v139 offset:49152
	ds_read_b128 v[176:179], v139 offset:50176
	ds_read_b128 v[180:183], v139 offset:51200
	ds_read_b128 v[184:187], v139 offset:52224
	ds_read_b128 v[188:191], v139 offset:53248
	ds_read_b128 v[192:195], v139 offset:54272
	ds_read_b128 v[196:199], v139 offset:55296
	ds_read_b128 v[200:203], v139 offset:56320
	s_mov_b32 m0, s47
	s_nop 0
	global_load_lds_dwordx4 v204, s[26:27]
	v_mov_b32_e32 v204, v136
	s_add_i32 m0, s47, 0x2000
	s_add_u32 s24, s24, 0x100080
	global_load_lds_dwordx4 v204, s[26:27]
	s_addc_u32 s25, s25, 0
	v_mov_b32_e32 v204, v134
	s_add_i32 s26, s48, s30
	s_mov_b32 m0, s26
	s_nop 0
	global_load_lds_dwordx4 v204, s[24:25]
	v_mov_b32_e32 v204, v136
	s_add_i32 m0, s26, 0x2000
	s_nop 0
	global_load_lds_dwordx4 v204, s[24:25]
	v_mov_b32_e32 v204, v133
	s_mov_b32 m0, s39
	s_nop 0
	global_load_lds_dwordx4 v204, s[22:23]
	v_mov_b32_e32 v204, v135
	s_mov_b32 m0, s40
	s_nop 0
	global_load_lds_dwordx4 v204, s[22:23]
	s_waitcnt vmcnt(8)
	s_waitcnt lgkmcnt(0)
	s_barrier
	s_setprio 1
	s_waitcnt lgkmcnt(0)
	v_mfma_f32_16x16x32_bf16 v[60:63], v[140:143], v[172:175], v[60:63]
	v_mfma_f32_16x16x32_bf16 v[56:59], v[148:151], v[172:175], v[56:59]
	v_mfma_f32_16x16x32_bf16 v[44:47], v[140:143], v[180:183], v[44:47]
	v_mfma_f32_16x16x32_bf16 v[40:43], v[148:151], v[180:183], v[40:43]
	v_mfma_f32_16x16x32_bf16 v[28:31], v[140:143], v[188:191], v[28:31]
	v_mfma_f32_16x16x32_bf16 v[24:27], v[148:151], v[188:191], v[24:27]
	v_mfma_f32_16x16x32_bf16 v[12:15], v[140:143], v[196:199], v[12:15]
	v_mfma_f32_16x16x32_bf16 v[8:11], v[148:151], v[196:199], v[8:11]
	v_mfma_f32_16x16x32_bf16 v[60:63], v[144:147], v[176:179], v[60:63]
	v_mfma_f32_16x16x32_bf16 v[56:59], v[152:155], v[176:179], v[56:59]
	v_mfma_f32_16x16x32_bf16 v[44:47], v[144:147], v[184:187], v[44:47]
	v_mfma_f32_16x16x32_bf16 v[40:43], v[152:155], v[184:187], v[40:43]
	v_mfma_f32_16x16x32_bf16 v[28:31], v[144:147], v[192:195], v[28:31]
	v_mfma_f32_16x16x32_bf16 v[24:27], v[152:155], v[192:195], v[24:27]
	v_mfma_f32_16x16x32_bf16 v[12:15], v[144:147], v[200:203], v[12:15]
	v_mfma_f32_16x16x32_bf16 v[8:11], v[152:155], v[200:203], v[8:11]
	s_setprio 0
	s_setprio 1
	v_mfma_f32_16x16x32_bf16 v[52:55], v[156:159], v[172:175], v[52:55]
	v_mfma_f32_16x16x32_bf16 v[48:51], v[164:167], v[172:175], v[48:51]
	v_mfma_f32_16x16x32_bf16 v[36:39], v[156:159], v[180:183], v[36:39]
	v_mfma_f32_16x16x32_bf16 v[32:35], v[164:167], v[180:183], v[32:35]
	v_mfma_f32_16x16x32_bf16 v[20:23], v[156:159], v[188:191], v[20:23]
	v_mfma_f32_16x16x32_bf16 v[16:19], v[164:167], v[188:191], v[16:19]
	v_mfma_f32_16x16x32_bf16 v[4:7], v[156:159], v[196:199], v[4:7]
	v_mfma_f32_16x16x32_bf16 v[0:3], v[164:167], v[196:199], v[0:3]
	v_mfma_f32_16x16x32_bf16 v[52:55], v[160:163], v[176:179], v[52:55]
	v_mfma_f32_16x16x32_bf16 v[48:51], v[168:171], v[176:179], v[48:51]
	v_mfma_f32_16x16x32_bf16 v[36:39], v[160:163], v[184:187], v[36:39]
	v_mfma_f32_16x16x32_bf16 v[32:35], v[168:171], v[184:187], v[32:35]
	v_mfma_f32_16x16x32_bf16 v[20:23], v[160:163], v[192:195], v[20:23]
	v_mfma_f32_16x16x32_bf16 v[16:19], v[168:171], v[192:195], v[16:19]
	v_mfma_f32_16x16x32_bf16 v[4:7], v[160:163], v[200:203], v[4:7]
	v_mfma_f32_16x16x32_bf16 v[0:3], v[168:171], v[200:203], v[0:3]
	s_setprio 0
	s_barrier
	s_add_i32 s46, s46, 2
	s_add_u32 s20, s20, 0x100
	s_addc_u32 s21, s21, 0
	s_cmp_gt_u32 s46, 61
.LBB0_974:
	s_add_u32 s47, s12, s20
	s_addc_u32 s49, s13, s21
	s_add_u32 s22, s47, 0x100
	s_addc_u32 s23, s49, 0
	v_add_u32_e32 v152, s41, v138
	v_add_u32_e32 v168, s42, v138
	s_add_u32 s24, s10, s20
	ds_read_b128 v[140:143], v152
	ds_read_b128 v[144:147], v152 offset:1024
	ds_read_b128 v[148:151], v152 offset:2048
	ds_read_b128 v[152:155], v152 offset:3072
	ds_read_b128 v[156:159], v168
	ds_read_b128 v[160:163], v168 offset:1024
	ds_read_b128 v[164:167], v168 offset:2048
	ds_read_b128 v[168:171], v168 offset:3072
	s_addc_u32 s25, s11, s21
	s_add_u32 s24, s24, 0x100
	s_addc_u32 s25, s25, 0
	s_cmp_eq_u32 s46, 60
	s_cselect_b32 s26, s44, s22
	s_cselect_b32 s27, s17, s23
	s_cselect_b32 s24, s45, s24
	s_cselect_b32 s25, s15, s25
	s_add_u32 s22, s26, 0x80
	s_addc_u32 s23, s27, 0
	s_add_u32 s48, s47, 0x100080
	s_addc_u32 s49, s49, 0
	v_mov_b32_e32 v204, v133
	s_waitcnt lgkmcnt(7)
	ds_read_b128 v[172:175], v139
	ds_read_b128 v[176:179], v139 offset:1024
	ds_read_b128 v[180:183], v139 offset:2048
	ds_read_b128 v[184:187], v139 offset:3072
	ds_read_b128 v[188:191], v139 offset:4096
	ds_read_b128 v[192:195], v139 offset:5120
	ds_read_b128 v[196:199], v139 offset:6144
	ds_read_b128 v[200:203], v139 offset:7168
	s_add_i32 m0, s7, 0xc000
	s_nop 0
	global_load_lds_dwordx4 v204, s[48:49]
	v_mov_b32_e32 v204, v135
	s_add_i32 m0, s7, 0xe000
	s_nop 0
	global_load_lds_dwordx4 v204, s[48:49]
	s_waitcnt vmcnt(8)
	s_waitcnt lgkmcnt(0)
	s_barrier
; #define PG8_STAGE(bufoff, gbase, voff) do { const char* gb_ = (const char*)(gbase); asm volatile("" : "+s"(gb_)); _Pragma("unroll") for (int _i = 0; _i < 2; ++_i) { unsigned vo_ = (voff)[_i]; asm volatile("" : "+v"(vo_)); \
;         __builtin_amdgcn_global_load_lds((const unsigned*)(gb_ + vo_), (PG8_LAS unsigned*)(lds + (bufoff) + ldsw + _i * 8192), 16, 0, 0); } } while (0)
; #define PG8_LDA(dst, b, h) do { _Pragma("unroll") for (int m = 0; m < 4; ++m) _Pragma("unroll") for (int k = 0; k < 2; ++k) dst[m][k] = *(const PG8_LAS bf16x8*)(lds + PG8_SA(b, h) + aoff + m * 2048 + k * 1024); } while (0)
; #define PG8_LDB(dst, b, h) do { _Pragma("unroll") for (int n = 0; n < 2; ++n) _Pragma("unroll") for (int k = 0; k < 2; ++k) dst[n][k] = *(const PG8_LAS bf16x8*)(lds + PG8_SB(b, h) + boff + n * 2048 + k * 1024); } while (0)
; #define PG8_MMA(ai, bj, At, Bt) do { __builtin_amdgcn_s_setprio(1); _Pragma("unroll") for (int m = 0; m < 4; ++m) _Pragma("unroll") for (int n = 0; n < 2; ++n) _Pragma("unroll") for (int k = 0; k < 2; ++k) \
;         acc[ai][bj][m][n] = __builtin_amdgcn_mfma_f32_16x16x32_bf16(Bt[n][k], At[m][k], acc[ai][bj][m][n], 0, 0, 0); __builtin_amdgcn_s_setprio(0); } while (0)
; #define PG8_WAIT_V(n) asm volatile("s_waitcnt vmcnt(" #n ")" ::: "memory")
; #define PG8_WAIT_L(n) asm volatile("s_waitcnt lgkmcnt(" #n ")" ::: "memory")
; #define PG8_BAR __builtin_amdgcn_s_barrier()
; #define PG8_SCHED __builtin_amdgcn_sched_barrier(0)
;     ...
;             PG8_LDB(B0, 0, 0); PG8_LDB(B1, 0, 1); PG8_SCHED; PG8_LDA(At, 0, 0); PG8_STAGE(PG8_SA(1, 1), a1 + hstep, voffA);
;             PG8_WAIT_V(8); PG8_WAIT_L(0); PG8_BAR; PG8_MMA(0, 0, At, B0); PG8_MMA(0, 1, At, B1); PG8_BAR; PG8_SCHED;
;             PG8_LDA(At, 0, 1); PG8_STAGE(PG8_SB(0, 0), b2, voffB); PG8_STAGE(PG8_SB(0, 1), b2 + hstepB, voffB); PG8_STAGE(PG8_SA(0, 0), a2, voffA);
;             PG8_WAIT_V(8); PG8_WAIT_L(0); PG8_BAR; PG8_MMA(1, 0, At, B0); PG8_MMA(1, 1, At, B1); PG8_BAR; PG8_SCHED;
	s_setprio 1
	s_waitcnt lgkmcnt(0)
	v_mfma_f32_16x16x32_bf16 v[124:127], v[140:143], v[172:175], v[124:127]
	v_mfma_f32_16x16x32_bf16 v[120:123], v[148:151], v[172:175], v[120:123]
	v_mfma_f32_16x16x32_bf16 v[108:111], v[140:143], v[180:183], v[108:111]
	v_mfma_f32_16x16x32_bf16 v[104:107], v[148:151], v[180:183], v[104:107]
	v_mfma_f32_16x16x32_bf16 v[92:95], v[140:143], v[188:191], v[92:95]
	v_mfma_f32_16x16x32_bf16 v[88:91], v[148:151], v[188:191], v[88:91]
	v_mfma_f32_16x16x32_bf16 v[76:79], v[140:143], v[196:199], v[76:79]
	v_mfma_f32_16x16x32_bf16 v[72:75], v[148:151], v[196:199], v[72:75]
	v_mfma_f32_16x16x32_bf16 v[124:127], v[144:147], v[176:179], v[124:127]
	v_mfma_f32_16x16x32_bf16 v[120:123], v[152:155], v[176:179], v[120:123]
	v_mfma_f32_16x16x32_bf16 v[108:111], v[144:147], v[184:187], v[108:111]
	v_mfma_f32_16x16x32_bf16 v[104:107], v[152:155], v[184:187], v[104:107]
	v_mfma_f32_16x16x32_bf16 v[92:95], v[144:147], v[192:195], v[92:95]
	v_mfma_f32_16x16x32_bf16 v[88:91], v[152:155], v[192:195], v[88:91]
	v_mfma_f32_16x16x32_bf16 v[76:79], v[144:147], v[200:203], v[76:79]
	v_mfma_f32_16x16x32_bf16 v[72:75], v[152:155], v[200:203], v[72:75]
	s_setprio 0
	s_setprio 1
	v_mfma_f32_16x16x32_bf16 v[116:119], v[156:159], v[172:175], v[116:119]
	v_mfma_f32_16x16x32_bf16 v[112:115], v[164:167], v[172:175], v[112:115]
	v_mfma_f32_16x16x32_bf16 v[100:103], v[156:159], v[180:183], v[100:103]
	v_mfma_f32_16x16x32_bf16 v[96:99], v[164:167], v[180:183], v[96:99]
	v_mfma_f32_16x16x32_bf16 v[84:87], v[156:159], v[188:191], v[84:87]
	v_mfma_f32_16x16x32_bf16 v[80:83], v[164:167], v[188:191], v[80:83]
	v_mfma_f32_16x16x32_bf16 v[68:71], v[156:159], v[196:199], v[68:71]
	v_mfma_f32_16x16x32_bf16 v[64:67], v[164:167], v[196:199], v[64:67]
	v_mfma_f32_16x16x32_bf16 v[116:119], v[160:163], v[176:179], v[116:119]
	v_mfma_f32_16x16x32_bf16 v[112:115], v[168:171], v[176:179], v[112:115]
	v_mfma_f32_16x16x32_bf16 v[100:103], v[160:163], v[184:187], v[100:103]
	v_mfma_f32_16x16x32_bf16 v[96:99], v[168:171], v[184:187], v[96:99]
	v_mfma_f32_16x16x32_bf16 v[84:87], v[160:163], v[192:195], v[84:87]
	v_mfma_f32_16x16x32_bf16 v[80:83], v[168:171], v[192:195], v[80:83]
	v_mfma_f32_16x16x32_bf16 v[68:71], v[160:163], v[200:203], v[68:71]
	v_mfma_f32_16x16x32_bf16 v[64:67], v[168:171], v[200:203], v[64:67]
	s_setprio 0
	s_barrier
	s_mov_b64 s[48:49], s[24:25]
	v_mov_b32_e32 v204, v134
	s_add_i32 s47, s41, s30
	ds_read_b128 v[172:175], v139 offset:16384
	ds_read_b128 v[176:179], v139 offset:17408
	ds_read_b128 v[180:183], v139 offset:18432
	ds_read_b128 v[184:187], v139 offset:19456
	ds_read_b128 v[188:191], v139 offset:20480
	ds_read_b128 v[192:195], v139 offset:21504
	ds_read_b128 v[196:199], v139 offset:22528
	ds_read_b128 v[200:203], v139 offset:23552
	s_mov_b32 m0, s47
	s_nop 0
	global_load_lds_dwordx4 v204, s[48:49]
	v_mov_b32_e32 v204, v136
	s_add_i32 m0, s47, 0x2000
	s_nop 0
	global_load_lds_dwordx4 v204, s[48:49]
	s_add_u32 s48, s24, 0x100000
	s_addc_u32 s49, s25, 0
	v_mov_b32_e32 v204, v134
	s_add_i32 s47, s42, s30
	s_mov_b32 m0, s47
	s_nop 0
	global_load_lds_dwordx4 v204, s[48:49]
	v_mov_b32_e32 v204, v136
	s_add_i32 m0, s47, 0x2000
	s_nop 0
	global_load_lds_dwordx4 v204, s[48:49]
	s_mov_b64 s[48:49], s[26:27]
	v_mov_b32_e32 v204, v133
	s_mov_b32 m0, s7
	s_nop 0
	global_load_lds_dwordx4 v204, s[48:49]
	v_mov_b32_e32 v204, v135
	s_mov_b32 m0, s31
	s_nop 0
	global_load_lds_dwordx4 v204, s[48:49]
	s_waitcnt vmcnt(8)
	s_waitcnt lgkmcnt(0)
	s_barrier
	s_setprio 1
	s_waitcnt lgkmcnt(0)
	v_mfma_f32_16x16x32_bf16 v[60:63], v[140:143], v[172:175], v[60:63]
	v_mfma_f32_16x16x32_bf16 v[56:59], v[148:151], v[172:175], v[56:59]
	v_mfma_f32_16x16x32_bf16 v[44:47], v[140:143], v[180:183], v[44:47]
	v_mfma_f32_16x16x32_bf16 v[40:43], v[148:151], v[180:183], v[40:43]
	v_mfma_f32_16x16x32_bf16 v[28:31], v[140:143], v[188:191], v[28:31]
	v_mfma_f32_16x16x32_bf16 v[24:27], v[148:151], v[188:191], v[24:27]
	v_mfma_f32_16x16x32_bf16 v[12:15], v[140:143], v[196:199], v[12:15]
	v_mfma_f32_16x16x32_bf16 v[8:11], v[148:151], v[196:199], v[8:11]
	v_mfma_f32_16x16x32_bf16 v[60:63], v[144:147], v[176:179], v[60:63]
	v_mfma_f32_16x16x32_bf16 v[56:59], v[152:155], v[176:179], v[56:59]
	v_mfma_f32_16x16x32_bf16 v[44:47], v[144:147], v[184:187], v[44:47]
	v_mfma_f32_16x16x32_bf16 v[40:43], v[152:155], v[184:187], v[40:43]
	v_mfma_f32_16x16x32_bf16 v[28:31], v[144:147], v[192:195], v[28:31]
	v_mfma_f32_16x16x32_bf16 v[24:27], v[152:155], v[192:195], v[24:27]
	v_mfma_f32_16x16x32_bf16 v[12:15], v[144:147], v[200:203], v[12:15]
	v_mfma_f32_16x16x32_bf16 v[8:11], v[152:155], v[200:203], v[8:11]
	s_setprio 0
	s_setprio 1
	v_mfma_f32_16x16x32_bf16 v[52:55], v[156:159], v[172:175], v[52:55]
	v_mfma_f32_16x16x32_bf16 v[48:51], v[164:167], v[172:175], v[48:51]
	v_mfma_f32_16x16x32_bf16 v[36:39], v[156:159], v[180:183], v[36:39]
	v_mfma_f32_16x16x32_bf16 v[32:35], v[164:167], v[180:183], v[32:35]
	v_mfma_f32_16x16x32_bf16 v[20:23], v[156:159], v[188:191], v[20:23]
	v_mfma_f32_16x16x32_bf16 v[16:19], v[164:167], v[188:191], v[16:19]
	v_mfma_f32_16x16x32_bf16 v[4:7], v[156:159], v[196:199], v[4:7]
	v_mfma_f32_16x16x32_bf16 v[0:3], v[164:167], v[196:199], v[0:3]
	v_mfma_f32_16x16x32_bf16 v[52:55], v[160:163], v[176:179], v[52:55]
	v_mfma_f32_16x16x32_bf16 v[48:51], v[168:171], v[176:179], v[48:51]
	v_mfma_f32_16x16x32_bf16 v[36:39], v[160:163], v[184:187], v[36:39]
	v_mfma_f32_16x16x32_bf16 v[32:35], v[168:171], v[184:187], v[32:35]
	v_mfma_f32_16x16x32_bf16 v[20:23], v[160:163], v[192:195], v[20:23]
	v_mfma_f32_16x16x32_bf16 v[16:19], v[168:171], v[192:195], v[16:19]
	v_mfma_f32_16x16x32_bf16 v[4:7], v[160:163], v[200:203], v[4:7]
	v_mfma_f32_16x16x32_bf16 v[0:3], v[168:171], v[200:203], v[0:3]
	s_setprio 0
	s_barrier
; #define PG8_STAGE(bufoff, gbase, voff) do { const char* gb_ = (const char*)(gbase); asm volatile("" : "+s"(gb_)); _Pragma("unroll") for (int _i = 0; _i < 2; ++_i) { unsigned vo_ = (voff)[_i]; asm volatile("" : "+v"(vo_)); \
;         __builtin_amdgcn_global_load_lds((const unsigned*)(gb_ + vo_), (PG8_LAS unsigned*)(lds + (bufoff) + ldsw + _i * 8192), 16, 0, 0); } } while (0)
; #define PG8_LDA(dst, b, h) do { _Pragma("unroll") for (int m = 0; m < 4; ++m) _Pragma("unroll") for (int k = 0; k < 2; ++k) dst[m][k] = *(const PG8_LAS bf16x8*)(lds + PG8_SA(b, h) + aoff + m * 2048 + k * 1024); } while (0)
; #define PG8_LDB(dst, b, h) do { _Pragma("unroll") for (int n = 0; n < 2; ++n) _Pragma("unroll") for (int k = 0; k < 2; ++k) dst[n][k] = *(const PG8_LAS bf16x8*)(lds + PG8_SB(b, h) + boff + n * 2048 + k * 1024); } while (0)
; #define PG8_MMA(ai, bj, At, Bt) do { __builtin_amdgcn_s_setprio(1); _Pragma("unroll") for (int m = 0; m < 4; ++m) _Pragma("unroll") for (int n = 0; n < 2; ++n) _Pragma("unroll") for (int k = 0; k < 2; ++k) \
;         acc[ai][bj][m][n] = __builtin_amdgcn_mfma_f32_16x16x32_bf16(Bt[n][k], At[m][k], acc[ai][bj][m][n], 0, 0, 0); __builtin_amdgcn_s_setprio(0); } while (0)
; #define PG8_WAIT_V(n) asm volatile("s_waitcnt vmcnt(" #n ")" ::: "memory")
; #define PG8_WAIT_L(n) asm volatile("s_waitcnt lgkmcnt(" #n ")" ::: "memory")
; #define PG8_BAR __builtin_amdgcn_s_barrier()
; #define PG8_SCHED __builtin_amdgcn_sched_barrier(0)
;     ...
;             PG8_LDB(B0, 1, 0); PG8_LDB(B1, 1, 1); PG8_SCHED; PG8_LDA(At, 1, 0); PG8_STAGE(PG8_SA(0, 1), a2 + hstep, voffA);
;             PG8_WAIT_V(8); PG8_WAIT_L(0); PG8_BAR; PG8_MMA(0, 0, At, B0); PG8_MMA(0, 1, At, B1); PG8_BAR; PG8_SCHED;
	s_add_i32 s47, 0, 0x18000
	s_add_i32 s48, 0, 0x1c000
	v_add_u32_e32 v152, s47, v138
	v_add_u32_e32 v168, s48, v138
	ds_read_b128 v[140:143], v152
	ds_read_b128 v[144:147], v152 offset:1024
	ds_read_b128 v[148:151], v152 offset:2048
	ds_read_b128 v[152:155], v152 offset:3072
	ds_read_b128 v[156:159], v168
	ds_read_b128 v[160:163], v168 offset:1024
	ds_read_b128 v[164:167], v168 offset:2048
	ds_read_b128 v[168:171], v168 offset:3072
	s_add_u32 s26, s26, 0x100000
	s_addc_u32 s27, s27, 0
	v_mov_b32_e32 v204, v133
	s_mov_b32 m0, s33
	ds_read_b128 v[172:175], v139 offset:32768
	ds_read_b128 v[176:179], v139 offset:33792
	ds_read_b128 v[180:183], v139 offset:34816
	ds_read_b128 v[184:187], v139 offset:35840
	ds_read_b128 v[188:191], v139 offset:36864
	ds_read_b128 v[192:195], v139 offset:37888
	ds_read_b128 v[196:199], v139 offset:38912
	ds_read_b128 v[200:203], v139 offset:39936
	s_nop 0
	global_load_lds_dwordx4 v204, s[26:27]
	v_mov_b32_e32 v204, v135
	s_mov_b32 m0, s35
	s_nop 0
	global_load_lds_dwordx4 v204, s[26:27]
	s_waitcnt vmcnt(8)
	s_waitcnt lgkmcnt(0)
	s_barrier
	s_setprio 1
	s_waitcnt lgkmcnt(0)
	v_mfma_f32_16x16x32_bf16 v[124:127], v[140:143], v[172:175], v[124:127]
	v_mfma_f32_16x16x32_bf16 v[120:123], v[148:151], v[172:175], v[120:123]
	v_mfma_f32_16x16x32_bf16 v[108:111], v[140:143], v[180:183], v[108:111]
	v_mfma_f32_16x16x32_bf16 v[104:107], v[148:151], v[180:183], v[104:107]
	v_mfma_f32_16x16x32_bf16 v[92:95], v[140:143], v[188:191], v[92:95]
	v_mfma_f32_16x16x32_bf16 v[88:91], v[148:151], v[188:191], v[88:91]
	v_mfma_f32_16x16x32_bf16 v[76:79], v[140:143], v[196:199], v[76:79]
	v_mfma_f32_16x16x32_bf16 v[72:75], v[148:151], v[196:199], v[72:75]
	v_mfma_f32_16x16x32_bf16 v[124:127], v[144:147], v[176:179], v[124:127]
	v_mfma_f32_16x16x32_bf16 v[120:123], v[152:155], v[176:179], v[120:123]
	v_mfma_f32_16x16x32_bf16 v[108:111], v[144:147], v[184:187], v[108:111]
	v_mfma_f32_16x16x32_bf16 v[104:107], v[152:155], v[184:187], v[104:107]
	v_mfma_f32_16x16x32_bf16 v[92:95], v[144:147], v[192:195], v[92:95]
	v_mfma_f32_16x16x32_bf16 v[88:91], v[152:155], v[192:195], v[88:91]
	v_mfma_f32_16x16x32_bf16 v[76:79], v[144:147], v[200:203], v[76:79]
	v_mfma_f32_16x16x32_bf16 v[72:75], v[152:155], v[200:203], v[72:75]
	s_setprio 0
	s_setprio 1
	v_mfma_f32_16x16x32_bf16 v[116:119], v[156:159], v[172:175], v[116:119]
	v_mfma_f32_16x16x32_bf16 v[112:115], v[164:167], v[172:175], v[112:115]
	v_mfma_f32_16x16x32_bf16 v[100:103], v[156:159], v[180:183], v[100:103]
	v_mfma_f32_16x16x32_bf16 v[96:99], v[164:167], v[180:183], v[96:99]
	v_mfma_f32_16x16x32_bf16 v[84:87], v[156:159], v[188:191], v[84:87]
	v_mfma_f32_16x16x32_bf16 v[80:83], v[164:167], v[188:191], v[80:83]
	v_mfma_f32_16x16x32_bf16 v[68:71], v[156:159], v[196:199], v[68:71]
	v_mfma_f32_16x16x32_bf16 v[64:67], v[164:167], v[196:199], v[64:67]
	v_mfma_f32_16x16x32_bf16 v[116:119], v[160:163], v[176:179], v[116:119]
	v_mfma_f32_16x16x32_bf16 v[112:115], v[168:171], v[176:179], v[112:115]
	v_mfma_f32_16x16x32_bf16 v[100:103], v[160:163], v[184:187], v[100:103]
	v_mfma_f32_16x16x32_bf16 v[96:99], v[168:171], v[184:187], v[96:99]
	v_mfma_f32_16x16x32_bf16 v[84:87], v[160:163], v[192:195], v[84:87]
	v_mfma_f32_16x16x32_bf16 v[80:83], v[168:171], v[192:195], v[80:83]
	v_mfma_f32_16x16x32_bf16 v[68:71], v[160:163], v[200:203], v[68:71]
	v_mfma_f32_16x16x32_bf16 v[64:67], v[168:171], v[200:203], v[64:67]
	s_setprio 0
	s_barrier
; #define PG8_STAGE(bufoff, gbase, voff) do { const char* gb_ = (const char*)(gbase); asm volatile("" : "+s"(gb_)); _Pragma("unroll") for (int _i = 0; _i < 2; ++_i) { unsigned vo_ = (voff)[_i]; asm volatile("" : "+v"(vo_)); \
;         __builtin_amdgcn_global_load_lds((const unsigned*)(gb_ + vo_), (PG8_LAS unsigned*)(lds + (bufoff) + ldsw + _i * 8192), 16, 0, 0); } } while (0)
; #define PG8_LDA(dst, b, h) do { _Pragma("unroll") for (int m = 0; m < 4; ++m) _Pragma("unroll") for (int k = 0; k < 2; ++k) dst[m][k] = *(const PG8_LAS bf16x8*)(lds + PG8_SA(b, h) + aoff + m * 2048 + k * 1024); } while (0)
; #define PG8_MMA(ai, bj, At, Bt) do { __builtin_amdgcn_s_setprio(1); _Pragma("unroll") for (int m = 0; m < 4; ++m) _Pragma("unroll") for (int n = 0; n < 2; ++n) _Pragma("unroll") for (int k = 0; k < 2; ++k) \
;         acc[ai][bj][m][n] = __builtin_amdgcn_mfma_f32_16x16x32_bf16(Bt[n][k], At[m][k], acc[ai][bj][m][n], 0, 0, 0); __builtin_amdgcn_s_setprio(0); } while (0)
; #define PG8_WAIT_V(n) asm volatile("s_waitcnt vmcnt(" #n ")" ::: "memory")
; #define PG8_WAIT_L(n) asm volatile("s_waitcnt lgkmcnt(" #n ")" ::: "memory")
; #define PG8_BAR __builtin_amdgcn_s_barrier()
; #define PG8_SCHED __builtin_amdgcn_sched_barrier(0)
;     ...
;             PG8_LDA(At, 1, 1); PG8_STAGE(PG8_SB(1, 0), b3, voffB); PG8_STAGE(PG8_SB(1, 1), b3 + hstepB, voffB); PG8_STAGE(PG8_SA(1, 0), a3, voffA);
;             PG8_WAIT_V(8); PG8_WAIT_L(0); PG8_BAR; PG8_MMA(1, 0, At, B0); PG8_MMA(1, 1, At, B1); PG8_BAR; PG8_SCHED;
;     ...
;         if constexpr (!Epi::KEEP_ACC) {
; #pragma unroll
;         for (int a = 0; a < 2; ++a)
; #pragma unroll
;             for (int b = 0; b < 2; ++b)
; #pragma unroll
;                 for (int m = 0; m < 4; ++m)
; #pragma unroll
;                     for (int n = 0; n < 2; ++n) acc[a][b][m][n] = (f32x4){0.f, 0.f, 0.f, 0.f};
;         }
;         cur = nxt; cA = nA; cB = nB; ++ui;
	s_add_u32 s26, s24, 0x80
	s_addc_u32 s27, s25, 0
	v_mov_b32_e32 v204, v134
	s_add_i32 s47, s47, s30
	ds_read_b128 v[172:175], v139 offset:49152
	ds_read_b128 v[176:179], v139 offset:50176
	ds_read_b128 v[180:183], v139 offset:51200
	ds_read_b128 v[184:187], v139 offset:52224
	ds_read_b128 v[188:191], v139 offset:53248
	ds_read_b128 v[192:195], v139 offset:54272
	ds_read_b128 v[196:199], v139 offset:55296
	ds_read_b128 v[200:203], v139 offset:56320
	s_mov_b32 m0, s47
	s_nop 0
	global_load_lds_dwordx4 v204, s[26:27]
	v_mov_b32_e32 v204, v136
	s_add_i32 m0, s47, 0x2000
	s_add_u32 s24, s24, 0x100080
	global_load_lds_dwordx4 v204, s[26:27]
	s_addc_u32 s25, s25, 0
	v_mov_b32_e32 v204, v134
	s_add_i32 s26, s48, s30
	s_mov_b32 m0, s26
	s_nop 0
	global_load_lds_dwordx4 v204, s[24:25]
	v_mov_b32_e32 v204, v136
	s_add_i32 m0, s26, 0x2000
	s_nop 0
	global_load_lds_dwordx4 v204, s[24:25]
	v_mov_b32_e32 v204, v133
	s_mov_b32 m0, s39
	s_nop 0
	global_load_lds_dwordx4 v204, s[22:23]
	v_mov_b32_e32 v204, v135
	s_mov_b32 m0, s40
	s_nop 0
	global_load_lds_dwordx4 v204, s[22:23]
	s_waitcnt vmcnt(8)
	s_waitcnt lgkmcnt(0)
	s_barrier
	s_setprio 1
	s_waitcnt lgkmcnt(0)
	v_mfma_f32_16x16x32_bf16 v[60:63], v[140:143], v[172:175], v[60:63]
	v_mfma_f32_16x16x32_bf16 v[56:59], v[148:151], v[172:175], v[56:59]
	v_mfma_f32_16x16x32_bf16 v[44:47], v[140:143], v[180:183], v[44:47]
	v_mfma_f32_16x16x32_bf16 v[40:43], v[148:151], v[180:183], v[40:43]
	v_mfma_f32_16x16x32_bf16 v[28:31], v[140:143], v[188:191], v[28:31]
	v_mfma_f32_16x16x32_bf16 v[24:27], v[148:151], v[188:191], v[24:27]
	v_mfma_f32_16x16x32_bf16 v[12:15], v[140:143], v[196:199], v[12:15]
	v_mfma_f32_16x16x32_bf16 v[8:11], v[148:151], v[196:199], v[8:11]
	v_mfma_f32_16x16x32_bf16 v[60:63], v[144:147], v[176:179], v[60:63]
	v_mfma_f32_16x16x32_bf16 v[56:59], v[152:155], v[176:179], v[56:59]
	v_mfma_f32_16x16x32_bf16 v[44:47], v[144:147], v[184:187], v[44:47]
	v_mfma_f32_16x16x32_bf16 v[40:43], v[152:155], v[184:187], v[40:43]
	v_mfma_f32_16x16x32_bf16 v[28:31], v[144:147], v[192:195], v[28:31]
	v_mfma_f32_16x16x32_bf16 v[24:27], v[152:155], v[192:195], v[24:27]
	v_mfma_f32_16x16x32_bf16 v[12:15], v[144:147], v[200:203], v[12:15]
	v_mfma_f32_16x16x32_bf16 v[8:11], v[152:155], v[200:203], v[8:11]
	s_setprio 0
	s_setprio 1
	v_mfma_f32_16x16x32_bf16 v[52:55], v[156:159], v[172:175], v[52:55]
	v_mfma_f32_16x16x32_bf16 v[48:51], v[164:167], v[172:175], v[48:51]
	v_mfma_f32_16x16x32_bf16 v[36:39], v[156:159], v[180:183], v[36:39]
	v_mfma_f32_16x16x32_bf16 v[32:35], v[164:167], v[180:183], v[32:35]
	v_mfma_f32_16x16x32_bf16 v[20:23], v[156:159], v[188:191], v[20:23]
	v_mfma_f32_16x16x32_bf16 v[16:19], v[164:167], v[188:191], v[16:19]
	v_mfma_f32_16x16x32_bf16 v[4:7], v[156:159], v[196:199], v[4:7]
	v_mfma_f32_16x16x32_bf16 v[0:3], v[164:167], v[196:199], v[0:3]
	v_mfma_f32_16x16x32_bf16 v[52:55], v[160:163], v[176:179], v[52:55]
	v_mfma_f32_16x16x32_bf16 v[48:51], v[168:171], v[176:179], v[48:51]
	v_mfma_f32_16x16x32_bf16 v[36:39], v[160:163], v[184:187], v[36:39]
	v_mfma_f32_16x16x32_bf16 v[32:35], v[168:171], v[184:187], v[32:35]
	v_mfma_f32_16x16x32_bf16 v[20:23], v[160:163], v[192:195], v[20:23]
	v_mfma_f32_16x16x32_bf16 v[16:19], v[168:171], v[192:195], v[16:19]
	v_mfma_f32_16x16x32_bf16 v[4:7], v[160:163], v[200:203], v[4:7]
	v_mfma_f32_16x16x32_bf16 v[0:3], v[168:171], v[200:203], v[0:3]
	s_setprio 0
	s_barrier
	s_add_i32 s46, s46, 2
	s_add_u32 s20, s20, 0x100
	s_addc_u32 s21, s21, 0
	s_cmp_gt_u32 s46, 61
	s_cbranch_scc0 .LBB0_974
	s_andn2_b64 vcc, exec, s[4:5]
	s_cbranch_vccnz .LBB0_966
	s_mov_b32 s34, s14
	s_mov_b32 s6, s16
	s_mov_b64 s[10:11], s[18:19]
	s_mov_b64 s[12:13], s[2:3]
	s_mov_b32 s38, s43
	s_branch .LBB0_966
